# v17 + in-proj epilogue kind 1: logf() expansion's denormal pre-scale and infinity pass-through removed (dead under the max(.,-60) clamp; stored values bit-identical)
# baseline (speedup 1.0000x reference)
;     template <int KIND>
;     __device__ __forceinline__ void run(const f32x4 (&acc)[2][2][4][2], const Unit& u, int wr, int wc, int fr, int fq) const {
;         const int row0 = u.pm * BM + wr * 64 + fr, col0 = u.pn * BM + wc * 32 + 8 * fq;
;         const float sa_lo = sa[u.pm * BM + wr * 64 + fr + 16 * fq], sa_hi = sa[u.pm * BM + HALF + wr * 64 + fr + 16 * fq];
; #pragma unroll
;         for (int bj = 0; bj < 2; ++bj) {
;             f32x2_t sc2[4], aux2[4];
; #pragma unroll
;             for (int j = 0; j < 4; ++j) {
;                 const float k0 = (KIND == 4) ? (0.125f * LOG2E / 127.0f) : (1.0f / 127.0f);
;                 sc2[j] = (f32x2_t){wmax[col0 + bj * HALF + 2 * j] * k0, wmax[col0 + bj * HALF + 2 * j + 1] * k0};
;                 if (KIND == 1) aux2[j] = (f32x2_t){lb[col0 - C_HG + bj * HALF + 2 * j], lb[col0 - C_HG + bj * HALF + 2 * j + 1]};
;                 else if (KIND == 3) aux2[j] = (f32x2_t){gain[col0 - C_HGATE + bj * HALF + 2 * j], gain[col0 - C_HGATE + bj * HALF + 2 * j + 1]};
;                 else aux2[j] = (f32x2_t){0.f, 0.f};
;             }
; #pragma unroll
;             for (int ai = 0; ai < 2; ++ai)
; #pragma unroll
;                 for (int m = 0; m < 4; ++m) { const int row = row0 + ai * HALF + m * 16; const float a = __shfl(ai ? sa_hi : sa_lo, 16 * m + fr);
;                     const f32x4 f0 = __builtin_convertvector(__builtin_bit_cast(i32x4, acc[ai][bj][m][0]), f32x4), f1 = __builtin_convertvector(__builtin_bit_cast(i32x4, acc[ai][bj][m][1]), f32x4);
;                     f32x2_t v[4] = {(f32x2_t){f0[0], f0[1]}, (f32x2_t){f0[2], f0[3]}, (f32x2_t){f1[0], f1[1]}, (f32x2_t){f1[2], f1[3]}};
; #pragma unroll
;                     for (int j = 0; j < 4; ++j) {
;                         v[j] = v[j] * (sc2[j] * (f32x2_t){a, a});
;                         if (KIND == 0 || KIND == 1 || KIND == 3) {
;                             const f32x2_t e = v[j] * (f32x2_t){-LOG2E, -LOG2E};
;                             const f32x2_t dn = (f32x2_t){__builtin_amdgcn_exp2f(e[0]), __builtin_amdgcn_exp2f(e[1])} + (f32x2_t){1.0f, 1.0f};
;                             const f32x2_t sg = (f32x2_t){fast_rcp(dn[0]), fast_rcp(dn[1])};
;                             if (KIND == 0) v[j] = v[j] * sg;
;                             else if (KIND == 3) v[j] = (v[j] * sg) * aux2[j];
.LBB0_224:
	s_andn2_b64 vcc, exec, s[0:1]
	s_cbranch_vccnz .LBB0_226
	s_mov_b32 s8, 0x3c010204
	s_waitcnt vmcnt(0)
	v_pk_mul_f32 v[188:189], v[154:155], s[8:9] op_sel_hi:[1,0]
	v_lshl_add_u64 v[154:155], v[146:147], 2, s[70:71]
	global_load_dwordx4 v[132:135], v[154:155], off offset:-2032
	global_load_dwordx4 v[136:139], v[154:155], off offset:-2048
	global_load_dwordx2 v[150:151], v[148:149], off offset:24
	global_load_dwordx4 v[156:159], v[148:149], off offset:8
	ds_bpermute_b32 v66, v210, v209
	v_cvt_f32_i32_e32 v161, v129
	v_cvt_f32_i32_e32 v160, v128
	s_mov_b32 s10, 0xbfb8aa3b
	s_mov_b32 s2, 0x800000
	s_waitcnt lgkmcnt(0)
	v_pk_mul_f32 v[166:167], v[188:189], v[66:67] op_sel_hi:[1,0]
	v_cvt_f32_i32_e32 v165, v131
	v_pk_mul_f32 v[160:161], v[160:161], v[166:167]
	v_cvt_f32_i32_e32 v164, v130
	v_pk_mul_f32 v[160:161], v[160:161], s[10:11] op_sel_hi:[1,0]
	s_mov_b32 s3, 0x3f317217
	v_exp_f32_e32 v160, v160
	v_exp_f32_e32 v161, v161
	s_mov_b32 s6, 0x7f800000
	v_mov_b64_e32 v[204:205], s[14:15]
	v_cvt_f32_i32_e32 v185, v97
	v_pk_add_f32 v[160:161], v[160:161], 1.0 op_sel_hi:[1,0]
	v_cvt_f32_i32_e32 v184, v96
	v_rcp_f32_e32 v160, v160
	v_rcp_f32_e32 v161, v161
	s_waitcnt vmcnt(3)
	v_pk_add_f32 v[194:195], v[132:133], 1.0 op_sel_hi:[1,0] neg_lo:[1,0] neg_hi:[1,0]
	s_waitcnt vmcnt(2)
	v_pk_add_f32 v[190:191], v[136:137], 1.0 op_sel_hi:[1,0] neg_lo:[1,0] neg_hi:[1,0]
	v_pk_add_f32 v[192:193], v[138:139], 1.0 op_sel_hi:[1,0] neg_lo:[1,0] neg_hi:[1,0]
	v_pk_fma_f32 v[160:161], v[190:191], v[160:161], v[136:137]
	s_waitcnt vmcnt(0)
	global_load_dwordx4 v[236:239], v[148:149], off offset:528
	global_load_dwordx4 v[240:243], v[148:149], off offset:512
	global_load_dwordx4 v[128:131], v[154:155], off offset:-1520
	global_load_dwordx4 v[244:247], v[154:155], off offset:-1536
	v_pk_mul_f32 v[180:181], v[156:157], s[8:9] op_sel_hi:[1,0]
	v_pk_mul_f32 v[166:167], v[180:181], v[66:67] op_sel_hi:[1,0]
	v_pk_mul_f32 v[170:171], v[158:159], s[8:9] op_sel_hi:[1,0]
	v_log_f32_e32 v160, v160
	v_pk_mul_f32 v[164:165], v[164:165], v[166:167]
	v_cvt_f32_i32_e32 v159, v125
	v_pk_mul_f32 v[164:165], v[164:165], s[10:11] op_sel_hi:[1,0]
	v_mul_f32_e32 v162, 0x3f317217, v160
	v_fma_f32 v162, v160, s3, -v162
	v_fmac_f32_e32 v162, 0x3377d1cf, v160
	v_fmac_f32_e32 v162, 0x3f317217, v160
	v_exp_f32_e32 v164, v164
	v_exp_f32_e32 v165, v165
	v_mov_b32_e32 v160, v162
	v_pk_add_f32 v[164:165], v[164:165], 1.0 op_sel_hi:[1,0]
	v_log_f32_e32 v161, v161
	v_rcp_f32_e32 v164, v164
	v_rcp_f32_e32 v165, v165
	v_cvt_f32_i32_e32 v158, v124
	v_mul_f32_e32 v162, 0x3f317217, v161
	v_fma_f32 v162, v161, s3, -v162
	v_fmac_f32_e32 v162, 0x3377d1cf, v161
	v_fmac_f32_e32 v162, 0x3f317217, v161
	v_pk_fma_f32 v[164:165], v[192:193], v[164:165], v[138:139]
	v_pk_mul_f32 v[166:167], v[170:171], v[66:67] op_sel_hi:[1,0]
	v_mov_b32_e32 v161, v162
	v_pk_mul_f32 v[158:159], v[158:159], v[166:167]
	v_log_f32_e32 v162, v164
	v_pk_mul_f32 v[158:159], v[158:159], s[10:11] op_sel_hi:[1,0]
	v_cvt_f32_i32_e32 v157, v127
	v_exp_f32_e32 v158, v158
	v_mul_f32_e32 v164, 0x3f317217, v162
	v_fma_f32 v164, v162, s3, -v164
	v_fmac_f32_e32 v164, 0x3377d1cf, v162
	v_fmac_f32_e32 v164, 0x3f317217, v162
	v_exp_f32_e32 v159, v159
	v_cvt_f32_i32_e32 v156, v126
	v_mov_b32_e32 v162, v164
	v_pk_add_f32 v[158:159], v[158:159], 1.0 op_sel_hi:[1,0]
	v_log_f32_e32 v164, v165
	v_rcp_f32_e32 v158, v158
	v_rcp_f32_e32 v159, v159
	v_pk_mul_f32 v[150:151], v[150:151], s[8:9] op_sel_hi:[1,0]
	v_mul_f32_e32 v165, 0x3f317217, v164
	v_fma_f32 v165, v164, s3, -v165
	v_fmac_f32_e32 v165, 0x3377d1cf, v164
	v_fmac_f32_e32 v165, 0x3f317217, v164
	v_pk_fma_f32 v[158:159], v[194:195], v[158:159], v[132:133]
	v_pk_add_f32 v[206:207], v[134:135], 1.0 op_sel_hi:[1,0] neg_lo:[1,0] neg_hi:[1,0]
	v_mov_b32_e32 v164, v165
	v_max_f32_e32 v160, 0xc2700000, v160
	v_log_f32_e32 v158, v158
	v_max_f32_e32 v161, 0xc2700000, v161
	v_max_f32_e32 v162, 0xc2700000, v162
	v_max_f32_e32 v164, 0xc2700000, v164
	v_mul_f32_e32 v165, 0x3f317217, v158
	v_fma_f32 v165, v158, s3, -v165
	v_fmac_f32_e32 v165, 0x3377d1cf, v158
	v_fmac_f32_e32 v165, 0x3f317217, v158
	s_nop 1
	v_mov_b32_e32 v158, v165
	v_max_f32_e32 v165, 0xc2700000, v158
	s_nop 0
	v_log_f32_e32 v158, v159
	s_nop 0
	v_mul_f32_e32 v159, 0x3f317217, v158
	v_fma_f32 v159, v158, s3, -v159
	v_fmac_f32_e32 v159, 0x3377d1cf, v158
	v_fmac_f32_e32 v159, 0x3f317217, v158
	s_nop 1
	v_mov_b32_e32 v158, v159
	v_max_f32_e32 v166, 0xc2700000, v158
	v_pk_mul_f32 v[158:159], v[150:151], v[66:67] op_sel_hi:[1,0]
	s_nop 0
	v_pk_mul_f32 v[156:157], v[156:157], v[158:159]
	s_nop 0
	v_pk_mul_f32 v[156:157], v[156:157], s[10:11] op_sel_hi:[1,0]
	s_nop 0
	v_exp_f32_e32 v156, v156
	v_exp_f32_e32 v157, v157
	s_nop 0
	v_pk_add_f32 v[156:157], v[156:157], 1.0 op_sel_hi:[1,0]
	s_nop 0
	v_rcp_f32_e32 v156, v156
	v_rcp_f32_e32 v157, v157
	s_nop 0
	v_pk_fma_f32 v[156:157], v[206:207], v[156:157], v[134:135]
	s_nop 0
	s_nop 1
	v_log_f32_e32 v156, v156
	s_nop 0
	v_mul_f32_e32 v158, 0x3f317217, v156
	v_fma_f32 v158, v156, s3, -v158
	v_fmac_f32_e32 v158, 0x3377d1cf, v156
	v_fmac_f32_e32 v158, 0x3f317217, v156
	s_nop 1
	v_mov_b32_e32 v156, v158
	v_max_f32_e32 v159, 0xc2700000, v156
	v_cvt_pk_bf16_f32 v158, v165, v166
	v_log_f32_e32 v156, v157
	v_cvt_f32_i32_e32 v166, v120
	v_cvt_f32_i32_e32 v165, v123
	v_mul_f32_e32 v157, 0x3f317217, v156
	v_fma_f32 v157, v156, s3, -v157
	v_fmac_f32_e32 v157, 0x3377d1cf, v156
	v_fmac_f32_e32 v157, 0x3f317217, v156
	s_nop 1
	v_mov_b32_e32 v156, v157
	v_max_f32_e32 v167, 0xc2700000, v156
	v_cvt_pk_bf16_f32 v156, v160, v161
	v_mad_i64_i32 v[160:161], s[0:1], v175, s81, v[204:205]
	v_cvt_pk_bf16_f32 v157, v162, v164
	v_cvt_pk_bf16_f32 v159, v159, v167
	v_lshl_add_u64 v[172:173], v[160:161], 0, v[152:153]
	global_store_dwordx4 v[172:173], v[156:159], off
	ds_bpermute_b32 v156, v210, v209 offset:64
	v_cvt_f32_i32_e32 v167, v121
	v_cvt_f32_i32_e32 v164, v122
	v_cvt_f32_i32_e32 v161, v117
	v_cvt_f32_i32_e32 v160, v116
	s_waitcnt lgkmcnt(0)
; __device__ __forceinline__ unsigned cvt_pk_bf16(float lo, float hi) { f32x2_t v = {lo, hi}; bf16x2_t b = __builtin_convertvector(v, bf16x2_t); return __builtin_bit_cast(unsigned, b); }
; __device__ __forceinline__ float fast_rcp(float x) { return __builtin_amdgcn_rcpf(x); }
;     template <int KIND>
;     __device__ __forceinline__ void run(const f32x4 (&acc)[2][2][4][2], const Unit& u, int wr, int wc, int fr, int fq) const {
;     ...
;                 for (int m = 0; m < 4; ++m) { const int row = row0 + ai * HALF + m * 16; const float a = __shfl(ai ? sa_hi : sa_lo, 16 * m + fr);
;                     const f32x4 f0 = __builtin_convertvector(__builtin_bit_cast(i32x4, acc[ai][bj][m][0]), f32x4), f1 = __builtin_convertvector(__builtin_bit_cast(i32x4, acc[ai][bj][m][1]), f32x4);
;                     f32x2_t v[4] = {(f32x2_t){f0[0], f0[1]}, (f32x2_t){f0[2], f0[3]}, (f32x2_t){f1[0], f1[1]}, (f32x2_t){f1[2], f1[3]}};
; #pragma unroll
;                     for (int j = 0; j < 4; ++j) {
;                         v[j] = v[j] * (sc2[j] * (f32x2_t){a, a});
;                         if (KIND == 0 || KIND == 1 || KIND == 3) {
;                             const f32x2_t e = v[j] * (f32x2_t){-LOG2E, -LOG2E};
;                             const f32x2_t dn = (f32x2_t){__builtin_amdgcn_exp2f(e[0]), __builtin_amdgcn_exp2f(e[1])} + (f32x2_t){1.0f, 1.0f};
;                             const f32x2_t sg = (f32x2_t){fast_rcp(dn[0]), fast_rcp(dn[1])};
;                             if (KIND == 0) v[j] = v[j] * sg;
;                             else if (KIND == 3) v[j] = (v[j] * sg) * aux2[j];
;                             else { const f32x2_t f = __builtin_elementwise_fma((f32x2_t){1.0f, 1.0f} - aux2[j], sg, aux2[j]);
;                                 v[j] = (f32x2_t){fmaxf(__logf(f[0]), -60.0f), fmaxf(__logf(f[1]), -60.0f)}; }
;                         }
;                     }
;                     u32x4 w; w.x = cvt_pk_bf16(v[0][0], v[0][1]); w.y = cvt_pk_bf16(v[1][0], v[1][1]); w.z = cvt_pk_bf16(v[2][0], v[2][1]); w.w = cvt_pk_bf16(v[3][0], v[3][1]);
;                     *(u32x4*)(O + (size_t)row * NPROJ + col0 + bj * HALF) = w; }
	v_pk_mul_f32 v[174:175], v[188:189], v[156:157] op_sel_hi:[1,0]
	v_cvt_f32_i32_e32 v159, v119
	v_pk_mul_f32 v[166:167], v[166:167], v[174:175]
	v_cvt_f32_i32_e32 v158, v118
	v_pk_mul_f32 v[166:167], v[166:167], s[10:11] op_sel_hi:[1,0]
	s_nop 0
	v_exp_f32_e32 v166, v166
	v_exp_f32_e32 v167, v167
	s_nop 0
	v_pk_add_f32 v[166:167], v[166:167], 1.0 op_sel_hi:[1,0]
	s_nop 0
	v_rcp_f32_e32 v166, v166
	v_rcp_f32_e32 v167, v167
	s_nop 0
	v_pk_fma_f32 v[166:167], v[190:191], v[166:167], v[136:137]
	s_nop 0
	s_nop 1
	v_log_f32_e32 v157, v166
	s_nop 0
	v_mul_f32_e32 v162, 0x3f317217, v157
	v_fma_f32 v162, v157, s3, -v162
	v_fmac_f32_e32 v162, 0x3377d1cf, v157
	v_fmac_f32_e32 v162, 0x3f317217, v157
	s_nop 1
	v_mov_b32_e32 v157, v162
	v_max_f32_e32 v157, 0xc2700000, v157
	v_log_f32_e32 v162, v167
	s_nop 0
	v_mul_f32_e32 v166, 0x3f317217, v162
	v_fma_f32 v166, v162, s3, -v166
	v_fmac_f32_e32 v166, 0x3377d1cf, v162
	v_fmac_f32_e32 v166, 0x3f317217, v162
	s_nop 1
	v_mov_b32_e32 v162, v166
	v_pk_mul_f32 v[166:167], v[180:181], v[156:157] op_sel_hi:[1,0]
	v_max_f32_e32 v162, 0xc2700000, v162
	v_pk_mul_f32 v[164:165], v[164:165], v[166:167]
	s_nop 0
	v_pk_mul_f32 v[164:165], v[164:165], s[10:11] op_sel_hi:[1,0]
	s_nop 0
	v_exp_f32_e32 v164, v164
	v_exp_f32_e32 v165, v165
	s_nop 0
	v_pk_add_f32 v[164:165], v[164:165], 1.0 op_sel_hi:[1,0]
	s_nop 0
	v_rcp_f32_e32 v164, v164
	v_rcp_f32_e32 v165, v165
	s_nop 0
	v_pk_fma_f32 v[164:165], v[192:193], v[164:165], v[138:139]
	s_nop 0
	s_nop 1
	v_log_f32_e32 v164, v164
	s_nop 0
	v_mul_f32_e32 v166, 0x3f317217, v164
	v_fma_f32 v166, v164, s3, -v166
	v_fmac_f32_e32 v166, 0x3377d1cf, v164
	v_fmac_f32_e32 v166, 0x3f317217, v164
	s_nop 1
	v_mov_b32_e32 v164, v166
	v_max_f32_e32 v166, 0xc2700000, v164
	s_nop 0
	v_log_f32_e32 v164, v165
	s_nop 0
	v_mul_f32_e32 v165, 0x3f317217, v164
	v_fma_f32 v165, v164, s3, -v165
	v_fmac_f32_e32 v165, 0x3377d1cf, v164
	v_fmac_f32_e32 v165, 0x3f317217, v164
	s_nop 1
	v_mov_b32_e32 v164, v165
	v_max_f32_e32 v167, 0xc2700000, v164
	v_pk_mul_f32 v[164:165], v[170:171], v[156:157] op_sel_hi:[1,0]
	s_nop 0
	v_pk_mul_f32 v[160:161], v[160:161], v[164:165]
	s_nop 0
	v_pk_mul_f32 v[160:161], v[160:161], s[10:11] op_sel_hi:[1,0]
	s_nop 0
	v_exp_f32_e32 v160, v160
	v_exp_f32_e32 v161, v161
	s_nop 0
	v_pk_add_f32 v[160:161], v[160:161], 1.0 op_sel_hi:[1,0]
	s_nop 0
	v_rcp_f32_e32 v160, v160
	v_rcp_f32_e32 v161, v161
	s_nop 0
	v_pk_fma_f32 v[160:161], v[194:195], v[160:161], v[132:133]
	s_nop 0
	s_nop 1
	v_log_f32_e32 v160, v160
	s_nop 0
	v_mul_f32_e32 v164, 0x3f317217, v160
	v_fma_f32 v164, v160, s3, -v164
	v_fmac_f32_e32 v164, 0x3377d1cf, v160
	v_fmac_f32_e32 v164, 0x3f317217, v160
	s_nop 1
	v_mov_b32_e32 v160, v164
	v_max_f32_e32 v164, 0xc2700000, v160
	s_nop 0
	v_log_f32_e32 v160, v161
	s_nop 0
	v_mul_f32_e32 v161, 0x3f317217, v160
	v_fma_f32 v161, v160, s3, -v161
	v_fmac_f32_e32 v161, 0x3377d1cf, v160
	v_fmac_f32_e32 v161, 0x3f317217, v160
	s_nop 1
	v_mov_b32_e32 v160, v161
	v_max_f32_e32 v165, 0xc2700000, v160
	v_pk_mul_f32 v[160:161], v[150:151], v[156:157] op_sel_hi:[1,0]
	s_nop 0
	v_pk_mul_f32 v[158:159], v[158:159], v[160:161]
	s_nop 0
	v_pk_mul_f32 v[158:159], v[158:159], s[10:11] op_sel_hi:[1,0]
	s_nop 0
	v_exp_f32_e32 v158, v158
	v_exp_f32_e32 v159, v159
	s_nop 0
	v_pk_add_f32 v[158:159], v[158:159], 1.0 op_sel_hi:[1,0]
	s_nop 0
	v_rcp_f32_e32 v158, v158
	v_rcp_f32_e32 v159, v159
	s_nop 0
	v_pk_fma_f32 v[158:159], v[206:207], v[158:159], v[134:135]
	s_nop 0
	s_nop 1
	v_log_f32_e32 v158, v158
	s_nop 0
	v_mul_f32_e32 v160, 0x3f317217, v158
	v_fma_f32 v160, v158, s3, -v160
	v_fmac_f32_e32 v160, 0x3377d1cf, v158
	v_fmac_f32_e32 v160, 0x3f317217, v158
	s_nop 1
	v_mov_b32_e32 v158, v160
	v_max_f32_e32 v161, 0xc2700000, v158
	v_cvt_pk_bf16_f32 v160, v164, v165
	v_log_f32_e32 v158, v159
	v_cvt_f32_i32_e32 v165, v115
	v_cvt_f32_i32_e32 v164, v114
	v_mul_f32_e32 v159, 0x3f317217, v158
	v_fma_f32 v159, v158, s3, -v159
	v_fmac_f32_e32 v159, 0x3377d1cf, v158
	v_fmac_f32_e32 v159, 0x3f317217, v158
	s_nop 1
	v_mov_b32_e32 v158, v159
	v_max_f32_e32 v168, 0xc2700000, v158
	v_cvt_pk_bf16_f32 v158, v157, v162
	v_mad_i64_i32 v[162:163], s[0:1], v163, s81, v[204:205]
	v_cvt_pk_bf16_f32 v159, v166, v167
	v_cvt_pk_bf16_f32 v161, v161, v168
	v_lshl_add_u64 v[174:175], v[162:163], 0, v[152:153]
	global_store_dwordx4 v[174:175], v[158:161], off
	ds_bpermute_b32 v158, v210, v209 offset:128
	v_cvt_f32_i32_e32 v167, v113
	v_cvt_f32_i32_e32 v166, v112
	v_cvt_f32_i32_e32 v163, v109
	v_cvt_f32_i32_e32 v162, v108
	s_waitcnt lgkmcnt(0)
; __device__ __forceinline__ unsigned cvt_pk_bf16(float lo, float hi) { f32x2_t v = {lo, hi}; bf16x2_t b = __builtin_convertvector(v, bf16x2_t); return __builtin_bit_cast(unsigned, b); }
; __device__ __forceinline__ float fast_rcp(float x) { return __builtin_amdgcn_rcpf(x); }
;     template <int KIND>
;     __device__ __forceinline__ void run(const f32x4 (&acc)[2][2][4][2], const Unit& u, int wr, int wc, int fr, int fq) const {
;     ...
;                 for (int m = 0; m < 4; ++m) { const int row = row0 + ai * HALF + m * 16; const float a = __shfl(ai ? sa_hi : sa_lo, 16 * m + fr);
;                     const f32x4 f0 = __builtin_convertvector(__builtin_bit_cast(i32x4, acc[ai][bj][m][0]), f32x4), f1 = __builtin_convertvector(__builtin_bit_cast(i32x4, acc[ai][bj][m][1]), f32x4);
;                     f32x2_t v[4] = {(f32x2_t){f0[0], f0[1]}, (f32x2_t){f0[2], f0[3]}, (f32x2_t){f1[0], f1[1]}, (f32x2_t){f1[2], f1[3]}};
; #pragma unroll
;                     for (int j = 0; j < 4; ++j) {
;                         v[j] = v[j] * (sc2[j] * (f32x2_t){a, a});
;                         if (KIND == 0 || KIND == 1 || KIND == 3) {
;                             const f32x2_t e = v[j] * (f32x2_t){-LOG2E, -LOG2E};
;                             const f32x2_t dn = (f32x2_t){__builtin_amdgcn_exp2f(e[0]), __builtin_amdgcn_exp2f(e[1])} + (f32x2_t){1.0f, 1.0f};
;                             const f32x2_t sg = (f32x2_t){fast_rcp(dn[0]), fast_rcp(dn[1])};
;                             if (KIND == 0) v[j] = v[j] * sg;
;                             else if (KIND == 3) v[j] = (v[j] * sg) * aux2[j];
;                             else { const f32x2_t f = __builtin_elementwise_fma((f32x2_t){1.0f, 1.0f} - aux2[j], sg, aux2[j]);
;                                 v[j] = (f32x2_t){fmaxf(__logf(f[0]), -60.0f), fmaxf(__logf(f[1]), -60.0f)}; }
;                         }
;                     }
;                     u32x4 w; w.x = cvt_pk_bf16(v[0][0], v[0][1]); w.y = cvt_pk_bf16(v[1][0], v[1][1]); w.z = cvt_pk_bf16(v[2][0], v[2][1]); w.w = cvt_pk_bf16(v[3][0], v[3][1]);
;                     *(u32x4*)(O + (size_t)row * NPROJ + col0 + bj * HALF) = w; }
	v_pk_mul_f32 v[178:179], v[188:189], v[158:159] op_sel_hi:[1,0]
	v_cvt_f32_i32_e32 v161, v111
	v_pk_mul_f32 v[166:167], v[166:167], v[178:179]
	v_cvt_f32_i32_e32 v160, v110
	v_pk_mul_f32 v[166:167], v[166:167], s[10:11] op_sel_hi:[1,0]
	v_cvt_f32_i32_e32 v179, v105
	v_exp_f32_e32 v166, v166
	v_exp_f32_e32 v167, v167
	v_cvt_f32_i32_e32 v178, v104
	v_pk_add_f32 v[166:167], v[166:167], 1.0 op_sel_hi:[1,0]
	s_nop 0
	v_rcp_f32_e32 v166, v166
	v_rcp_f32_e32 v167, v167
	s_nop 0
	v_pk_fma_f32 v[166:167], v[190:191], v[166:167], v[136:137]
	s_nop 0
	s_nop 1
	v_log_f32_e32 v157, v166
	s_nop 0
	v_mul_f32_e32 v159, 0x3f317217, v157
	v_fma_f32 v159, v157, s3, -v159
	v_fmac_f32_e32 v159, 0x3377d1cf, v157
	v_fmac_f32_e32 v159, 0x3f317217, v157
	s_nop 1
	v_mov_b32_e32 v157, v159
	v_max_f32_e32 v157, 0xc2700000, v157
	v_log_f32_e32 v159, v167
	s_nop 0
	v_mul_f32_e32 v166, 0x3f317217, v159
	v_fma_f32 v166, v159, s3, -v166
	v_fmac_f32_e32 v166, 0x3377d1cf, v159
	v_fmac_f32_e32 v166, 0x3f317217, v159
	s_nop 1
	v_mov_b32_e32 v159, v166
	v_max_f32_e32 v159, 0xc2700000, v159
	v_pk_mul_f32 v[166:167], v[180:181], v[158:159] op_sel_hi:[1,0]
	s_nop 0
	v_pk_mul_f32 v[164:165], v[164:165], v[166:167]
	s_nop 0
	v_pk_mul_f32 v[164:165], v[164:165], s[10:11] op_sel_hi:[1,0]
	s_nop 0
	v_exp_f32_e32 v164, v164
	v_exp_f32_e32 v165, v165
	s_nop 0
	v_pk_add_f32 v[164:165], v[164:165], 1.0 op_sel_hi:[1,0]
	s_nop 0
	v_rcp_f32_e32 v164, v164
	v_rcp_f32_e32 v165, v165
	s_nop 0
	v_pk_fma_f32 v[164:165], v[192:193], v[164:165], v[138:139]
	s_nop 0
	s_nop 1
	v_log_f32_e32 v164, v164
	s_nop 0
	v_mul_f32_e32 v166, 0x3f317217, v164
	v_fma_f32 v166, v164, s3, -v166
	v_fmac_f32_e32 v166, 0x3377d1cf, v164
	v_fmac_f32_e32 v166, 0x3f317217, v164
	s_nop 1
	v_mov_b32_e32 v164, v166
	v_max_f32_e32 v166, 0xc2700000, v164
	s_nop 0
	v_log_f32_e32 v164, v165
	s_nop 0
	v_mul_f32_e32 v165, 0x3f317217, v164
	v_fma_f32 v165, v164, s3, -v165
	v_fmac_f32_e32 v165, 0x3377d1cf, v164
	v_fmac_f32_e32 v165, 0x3f317217, v164
	s_nop 1
	v_mov_b32_e32 v164, v165
	v_max_f32_e32 v167, 0xc2700000, v164
	v_pk_mul_f32 v[164:165], v[170:171], v[158:159] op_sel_hi:[1,0]
	s_nop 0
	v_pk_mul_f32 v[162:163], v[162:163], v[164:165]
	s_nop 0
	v_pk_mul_f32 v[162:163], v[162:163], s[10:11] op_sel_hi:[1,0]
	s_nop 0
	v_exp_f32_e32 v162, v162
	v_exp_f32_e32 v163, v163
	s_nop 0
	v_pk_add_f32 v[162:163], v[162:163], 1.0 op_sel_hi:[1,0]
	s_nop 0
	v_rcp_f32_e32 v162, v162
	v_rcp_f32_e32 v163, v163
	s_nop 0
	v_pk_fma_f32 v[162:163], v[194:195], v[162:163], v[132:133]
	s_nop 0
	s_nop 1
	v_log_f32_e32 v162, v162
	s_nop 0
	v_mul_f32_e32 v164, 0x3f317217, v162
	v_fma_f32 v164, v162, s3, -v164
	v_fmac_f32_e32 v164, 0x3377d1cf, v162
	v_fmac_f32_e32 v164, 0x3f317217, v162
	s_nop 1
	v_mov_b32_e32 v162, v164
	v_max_f32_e32 v164, 0xc2700000, v162
	s_nop 0
	v_log_f32_e32 v162, v163
	s_nop 0
	v_mul_f32_e32 v163, 0x3f317217, v162
	v_fma_f32 v163, v162, s3, -v163
	v_fmac_f32_e32 v163, 0x3377d1cf, v162
	v_fmac_f32_e32 v163, 0x3f317217, v162
	s_nop 1
	v_mov_b32_e32 v162, v163
	v_max_f32_e32 v165, 0xc2700000, v162
	v_pk_mul_f32 v[162:163], v[150:151], v[158:159] op_sel_hi:[1,0]
	s_nop 0
	v_pk_mul_f32 v[160:161], v[160:161], v[162:163]
	s_nop 0
	v_pk_mul_f32 v[160:161], v[160:161], s[10:11] op_sel_hi:[1,0]
	s_nop 0
	v_exp_f32_e32 v160, v160
	v_exp_f32_e32 v161, v161
	s_nop 0
	v_pk_add_f32 v[160:161], v[160:161], 1.0 op_sel_hi:[1,0]
	s_nop 0
	v_rcp_f32_e32 v160, v160
	v_rcp_f32_e32 v161, v161
	s_nop 0
	v_pk_fma_f32 v[160:161], v[206:207], v[160:161], v[134:135]
	s_nop 0
	s_nop 1
	v_log_f32_e32 v160, v160
	s_nop 0
	v_mul_f32_e32 v162, 0x3f317217, v160
	v_fma_f32 v162, v160, s3, -v162
	v_fmac_f32_e32 v162, 0x3377d1cf, v160
	v_fmac_f32_e32 v162, 0x3f317217, v160
	s_nop 1
	v_mov_b32_e32 v160, v162
	v_max_f32_e32 v163, 0xc2700000, v160
	v_cvt_pk_bf16_f32 v162, v164, v165
	v_log_f32_e32 v160, v161
	v_mad_i64_i32 v[164:165], s[0:1], v177, s81, v[204:205]
	v_lshl_add_u64 v[176:177], v[164:165], 0, v[152:153]
	v_mul_f32_e32 v161, 0x3f317217, v160
	v_fma_f32 v161, v160, s3, -v161
	v_fmac_f32_e32 v161, 0x3377d1cf, v160
	v_fmac_f32_e32 v161, 0x3f317217, v160
	v_cvt_f32_i32_e32 v165, v101
	v_cvt_f32_i32_e32 v164, v100
	v_mov_b32_e32 v160, v161
	v_max_f32_e32 v168, 0xc2700000, v160
	v_cvt_pk_bf16_f32 v160, v157, v159
	v_cvt_pk_bf16_f32 v161, v166, v167
	v_cvt_pk_bf16_f32 v163, v163, v168
	global_store_dwordx4 v[176:177], v[160:163], off
	ds_bpermute_b32 v160, v210, v209 offset:192
	v_cvt_f32_i32_e32 v167, v107
	v_cvt_f32_i32_e32 v166, v106
	v_cvt_f32_i32_e32 v163, v103
	v_cvt_f32_i32_e32 v162, v102
	s_waitcnt lgkmcnt(0)
; __device__ __forceinline__ unsigned cvt_pk_bf16(float lo, float hi) { f32x2_t v = {lo, hi}; bf16x2_t b = __builtin_convertvector(v, bf16x2_t); return __builtin_bit_cast(unsigned, b); }
; __device__ __forceinline__ float fast_rcp(float x) { return __builtin_amdgcn_rcpf(x); }
;     template <int KIND>
;     __device__ __forceinline__ void run(const f32x4 (&acc)[2][2][4][2], const Unit& u, int wr, int wc, int fr, int fq) const {
;     ...
;                 for (int m = 0; m < 4; ++m) { const int row = row0 + ai * HALF + m * 16; const float a = __shfl(ai ? sa_hi : sa_lo, 16 * m + fr);
;                     const f32x4 f0 = __builtin_convertvector(__builtin_bit_cast(i32x4, acc[ai][bj][m][0]), f32x4), f1 = __builtin_convertvector(__builtin_bit_cast(i32x4, acc[ai][bj][m][1]), f32x4);
;                     f32x2_t v[4] = {(f32x2_t){f0[0], f0[1]}, (f32x2_t){f0[2], f0[3]}, (f32x2_t){f1[0], f1[1]}, (f32x2_t){f1[2], f1[3]}};
; #pragma unroll
;                     for (int j = 0; j < 4; ++j) {
;                         v[j] = v[j] * (sc2[j] * (f32x2_t){a, a});
;                         if (KIND == 0 || KIND == 1 || KIND == 3) {
;                             const f32x2_t e = v[j] * (f32x2_t){-LOG2E, -LOG2E};
;                             const f32x2_t dn = (f32x2_t){__builtin_amdgcn_exp2f(e[0]), __builtin_amdgcn_exp2f(e[1])} + (f32x2_t){1.0f, 1.0f};
;                             const f32x2_t sg = (f32x2_t){fast_rcp(dn[0]), fast_rcp(dn[1])};
;                             if (KIND == 0) v[j] = v[j] * sg;
;                             else if (KIND == 3) v[j] = (v[j] * sg) * aux2[j];
;                             else { const f32x2_t f = __builtin_elementwise_fma((f32x2_t){1.0f, 1.0f} - aux2[j], sg, aux2[j]);
;                                 v[j] = (f32x2_t){fmaxf(__logf(f[0]), -60.0f), fmaxf(__logf(f[1]), -60.0f)}; }
;                         }
;                     }
;                     u32x4 w; w.x = cvt_pk_bf16(v[0][0], v[0][1]); w.y = cvt_pk_bf16(v[1][0], v[1][1]); w.z = cvt_pk_bf16(v[2][0], v[2][1]); w.w = cvt_pk_bf16(v[3][0], v[3][1]);
;                     *(u32x4*)(O + (size_t)row * NPROJ + col0 + bj * HALF) = w; }
	v_pk_mul_f32 v[182:183], v[188:189], v[160:161] op_sel_hi:[1,0]
	v_cvt_f32_i32_e32 v209, v71
	v_pk_mul_f32 v[178:179], v[178:179], v[182:183]
	v_cvt_f32_i32_e32 v183, v99
	v_pk_mul_f32 v[178:179], v[178:179], s[10:11] op_sel_hi:[1,0]
	v_cvt_f32_i32_e32 v182, v98
	v_exp_f32_e32 v178, v178
	v_exp_f32_e32 v179, v179
	s_nop 0
	v_pk_add_f32 v[178:179], v[178:179], 1.0 op_sel_hi:[1,0]
	s_nop 0
	v_rcp_f32_e32 v178, v178
	v_rcp_f32_e32 v179, v179
	s_nop 0
	v_pk_fma_f32 v[178:179], v[190:191], v[178:179], v[136:137]
	s_nop 0
	s_nop 1
	v_log_f32_e32 v157, v178
	s_nop 0
	v_mul_f32_e32 v159, 0x3f317217, v157
	v_fma_f32 v159, v157, s3, -v159
	v_fmac_f32_e32 v159, 0x3377d1cf, v157
	v_fmac_f32_e32 v159, 0x3f317217, v157
	s_nop 1
	v_mov_b32_e32 v157, v159
	v_max_f32_e32 v157, 0xc2700000, v157
	v_log_f32_e32 v159, v179
	s_nop 0
	v_mul_f32_e32 v161, 0x3f317217, v159
	v_fma_f32 v161, v159, s3, -v161
	v_fmac_f32_e32 v161, 0x3377d1cf, v159
	v_fmac_f32_e32 v161, 0x3f317217, v159
	s_nop 1
	v_mov_b32_e32 v159, v161
	v_pk_mul_f32 v[178:179], v[180:181], v[160:161] op_sel_hi:[1,0]
	v_pk_mul_f32 v[166:167], v[166:167], v[178:179]
	v_max_f32_e32 v159, 0xc2700000, v159
	v_pk_mul_f32 v[166:167], v[166:167], s[10:11] op_sel_hi:[1,0]
	s_nop 0
	v_exp_f32_e32 v166, v166
	v_exp_f32_e32 v167, v167
	s_nop 0
	v_pk_add_f32 v[166:167], v[166:167], 1.0 op_sel_hi:[1,0]
	s_nop 0
	v_rcp_f32_e32 v166, v166
	v_rcp_f32_e32 v167, v167
	s_nop 0
	v_pk_fma_f32 v[166:167], v[192:193], v[166:167], v[138:139]
	s_nop 0
	s_nop 1
	v_log_f32_e32 v161, v166
	s_nop 0
	v_mul_f32_e32 v166, 0x3f317217, v161
	v_fma_f32 v166, v161, s3, -v166
	v_fmac_f32_e32 v166, 0x3377d1cf, v161
	v_fmac_f32_e32 v166, 0x3f317217, v161
	s_nop 1
	v_mov_b32_e32 v161, v166
	v_max_f32_e32 v161, 0xc2700000, v161
	v_log_f32_e32 v166, v167
	s_nop 0
	v_mul_f32_e32 v167, 0x3f317217, v166
	v_fma_f32 v167, v166, s3, -v167
	v_fmac_f32_e32 v167, 0x3377d1cf, v166
	v_fmac_f32_e32 v167, 0x3f317217, v166
	s_nop 1
	v_mov_b32_e32 v166, v167
	v_max_f32_e32 v168, 0xc2700000, v166
	v_pk_mul_f32 v[166:167], v[170:171], v[160:161] op_sel_hi:[1,0]
	s_nop 0
	v_pk_mul_f32 v[164:165], v[164:165], v[166:167]
	s_nop 0
	v_pk_mul_f32 v[164:165], v[164:165], s[10:11] op_sel_hi:[1,0]
	s_nop 0
	v_exp_f32_e32 v164, v164
	v_exp_f32_e32 v165, v165
	s_nop 0
	v_pk_add_f32 v[164:165], v[164:165], 1.0 op_sel_hi:[1,0]
	s_nop 0
	v_rcp_f32_e32 v164, v164
	v_rcp_f32_e32 v165, v165
	s_nop 0
	v_pk_fma_f32 v[164:165], v[194:195], v[164:165], v[132:133]
	s_nop 0
	s_nop 1
	v_log_f32_e32 v164, v164
	s_nop 0
	v_mul_f32_e32 v166, 0x3f317217, v164
	v_fma_f32 v166, v164, s3, -v166
	v_fmac_f32_e32 v166, 0x3377d1cf, v164
	v_fmac_f32_e32 v166, 0x3f317217, v164
	s_nop 1
	v_mov_b32_e32 v164, v166
	v_max_f32_e32 v166, 0xc2700000, v164
	s_nop 0
	v_log_f32_e32 v164, v165
	s_nop 0
	v_mul_f32_e32 v165, 0x3f317217, v164
	v_fma_f32 v165, v164, s3, -v165
	v_fmac_f32_e32 v165, 0x3377d1cf, v164
	v_fmac_f32_e32 v165, 0x3f317217, v164
	s_nop 1
	v_mov_b32_e32 v164, v165
	v_max_f32_e32 v167, 0xc2700000, v164
	v_pk_mul_f32 v[164:165], v[150:151], v[160:161] op_sel_hi:[1,0]
	s_nop 0
	v_pk_mul_f32 v[162:163], v[162:163], v[164:165]
	s_nop 0
	v_pk_mul_f32 v[162:163], v[162:163], s[10:11] op_sel_hi:[1,0]
	s_nop 0
	v_exp_f32_e32 v162, v162
	v_exp_f32_e32 v163, v163
	s_nop 0
	v_pk_add_f32 v[162:163], v[162:163], 1.0 op_sel_hi:[1,0]
	s_nop 0
	v_rcp_f32_e32 v162, v162
	v_rcp_f32_e32 v163, v163
	s_nop 0
	v_pk_fma_f32 v[162:163], v[206:207], v[162:163], v[134:135]
	s_nop 0
	s_nop 1
	v_log_f32_e32 v162, v162
	s_nop 0
	v_mul_f32_e32 v164, 0x3f317217, v162
	v_fma_f32 v164, v162, s3, -v164
	v_fmac_f32_e32 v164, 0x3377d1cf, v162
	v_fmac_f32_e32 v164, 0x3f317217, v162
	s_nop 1
	v_mov_b32_e32 v162, v164
	v_max_f32_e32 v165, 0xc2700000, v162
	v_cvt_pk_bf16_f32 v164, v166, v167
	v_log_f32_e32 v162, v163
	v_mad_i64_i32 v[166:167], s[0:1], v187, s81, v[204:205]
	v_cvt_f32_i32_e32 v187, v77
	v_mul_f32_e32 v163, 0x3f317217, v162
	v_fma_f32 v163, v162, s3, -v163
	v_fmac_f32_e32 v163, 0x3377d1cf, v162
	v_fmac_f32_e32 v163, 0x3f317217, v162
	s_nop 1
	v_mov_b32_e32 v162, v163
	v_max_f32_e32 v178, 0xc2700000, v162
	v_cvt_pk_bf16_f32 v162, v157, v159
	v_cvt_pk_bf16_f32 v163, v161, v168
	v_cvt_pk_bf16_f32 v165, v165, v178
	v_lshl_add_u64 v[178:179], v[166:167], 0, v[152:153]
	global_store_dwordx4 v[178:179], v[162:165], off
	ds_bpermute_b32 v162, v210, v208
	v_cvt_f32_i32_e32 v167, v93
	v_cvt_f32_i32_e32 v166, v92
	v_cvt_f32_i32_e32 v165, v95
	v_cvt_f32_i32_e32 v164, v94
	s_waitcnt lgkmcnt(0)
; __device__ __forceinline__ unsigned cvt_pk_bf16(float lo, float hi) { f32x2_t v = {lo, hi}; bf16x2_t b = __builtin_convertvector(v, bf16x2_t); return __builtin_bit_cast(unsigned, b); }
; __device__ __forceinline__ float fast_rcp(float x) { return __builtin_amdgcn_rcpf(x); }
;     template <int KIND>
;     __device__ __forceinline__ void run(const f32x4 (&acc)[2][2][4][2], const Unit& u, int wr, int wc, int fr, int fq) const {
;     ...
;                 for (int m = 0; m < 4; ++m) { const int row = row0 + ai * HALF + m * 16; const float a = __shfl(ai ? sa_hi : sa_lo, 16 * m + fr);
;                     const f32x4 f0 = __builtin_convertvector(__builtin_bit_cast(i32x4, acc[ai][bj][m][0]), f32x4), f1 = __builtin_convertvector(__builtin_bit_cast(i32x4, acc[ai][bj][m][1]), f32x4);
;                     f32x2_t v[4] = {(f32x2_t){f0[0], f0[1]}, (f32x2_t){f0[2], f0[3]}, (f32x2_t){f1[0], f1[1]}, (f32x2_t){f1[2], f1[3]}};
; #pragma unroll
;                     for (int j = 0; j < 4; ++j) {
;                         v[j] = v[j] * (sc2[j] * (f32x2_t){a, a});
;                         if (KIND == 0 || KIND == 1 || KIND == 3) {
;                             const f32x2_t e = v[j] * (f32x2_t){-LOG2E, -LOG2E};
;                             const f32x2_t dn = (f32x2_t){__builtin_amdgcn_exp2f(e[0]), __builtin_amdgcn_exp2f(e[1])} + (f32x2_t){1.0f, 1.0f};
;                             const f32x2_t sg = (f32x2_t){fast_rcp(dn[0]), fast_rcp(dn[1])};
;                             if (KIND == 0) v[j] = v[j] * sg;
;                             else if (KIND == 3) v[j] = (v[j] * sg) * aux2[j];
;                             else { const f32x2_t f = __builtin_elementwise_fma((f32x2_t){1.0f, 1.0f} - aux2[j], sg, aux2[j]);
;                                 v[j] = (f32x2_t){fmaxf(__logf(f[0]), -60.0f), fmaxf(__logf(f[1]), -60.0f)}; }
;                         }
;                     }
;                     u32x4 w; w.x = cvt_pk_bf16(v[0][0], v[0][1]); w.y = cvt_pk_bf16(v[1][0], v[1][1]); w.z = cvt_pk_bf16(v[2][0], v[2][1]); w.w = cvt_pk_bf16(v[3][0], v[3][1]);
;                     *(u32x4*)(O + (size_t)row * NPROJ + col0 + bj * HALF) = w; }
	v_pk_mul_f32 v[196:197], v[188:189], v[162:163] op_sel_hi:[1,0]
	s_nop 0
	v_pk_mul_f32 v[184:185], v[184:185], v[196:197]
	v_cvt_f32_i32_e32 v197, v89
	v_pk_mul_f32 v[184:185], v[184:185], s[10:11] op_sel_hi:[1,0]
	v_cvt_f32_i32_e32 v196, v88
	v_exp_f32_e32 v184, v184
	v_exp_f32_e32 v185, v185
	s_nop 0
	v_pk_add_f32 v[184:185], v[184:185], 1.0 op_sel_hi:[1,0]
	s_nop 0
	v_rcp_f32_e32 v184, v184
	v_rcp_f32_e32 v185, v185
	s_nop 0
	v_pk_fma_f32 v[184:185], v[190:191], v[184:185], v[136:137]
	s_nop 0
	s_nop 1
	v_log_f32_e32 v157, v184
	s_nop 0
	v_mul_f32_e32 v159, 0x3f317217, v157
	v_fma_f32 v159, v157, s3, -v159
	v_fmac_f32_e32 v159, 0x3377d1cf, v157
	v_fmac_f32_e32 v159, 0x3f317217, v157
	s_nop 1
	v_mov_b32_e32 v157, v159
	v_max_f32_e32 v157, 0xc2700000, v157
	v_log_f32_e32 v159, v185
	v_pk_mul_f32 v[184:185], v[180:181], v[162:163] op_sel_hi:[1,0]
	v_pk_mul_f32 v[182:183], v[182:183], v[184:185]
	v_cvt_f32_i32_e32 v185, v91
	v_pk_mul_f32 v[182:183], v[182:183], s[10:11] op_sel_hi:[1,0]
	v_mul_f32_e32 v161, 0x3f317217, v159
	v_exp_f32_e32 v182, v182
	v_exp_f32_e32 v183, v183
	v_fma_f32 v161, v159, s3, -v161
	v_fmac_f32_e32 v161, 0x3377d1cf, v159
	v_fmac_f32_e32 v161, 0x3f317217, v159
	v_pk_add_f32 v[182:183], v[182:183], 1.0 op_sel_hi:[1,0]
	v_rcp_f32_e32 v182, v182
	v_rcp_f32_e32 v183, v183
	v_mov_b32_e32 v159, v161
	v_pk_fma_f32 v[182:183], v[192:193], v[182:183], v[138:139]
	v_max_f32_e32 v159, 0xc2700000, v159
	v_cvt_f32_i32_e32 v184, v90
	s_nop 0
	v_log_f32_e32 v161, v182
	s_nop 0
	v_mul_f32_e32 v163, 0x3f317217, v161
	v_fma_f32 v163, v161, s3, -v163
	v_fmac_f32_e32 v163, 0x3377d1cf, v161
	v_fmac_f32_e32 v163, 0x3f317217, v161
	s_nop 1
	v_mov_b32_e32 v161, v163
	v_max_f32_e32 v161, 0xc2700000, v161
	v_log_f32_e32 v163, v183
	s_nop 0
	v_mul_f32_e32 v168, 0x3f317217, v163
	v_fma_f32 v168, v163, s3, -v168
	v_fmac_f32_e32 v168, 0x3377d1cf, v163
	v_fmac_f32_e32 v168, 0x3f317217, v163
	s_nop 1
	v_mov_b32_e32 v163, v168
	v_max_f32_e32 v163, 0xc2700000, v163
	v_pk_mul_f32 v[182:183], v[170:171], v[162:163] op_sel_hi:[1,0]
	s_nop 0
	v_pk_mul_f32 v[166:167], v[166:167], v[182:183]
	s_nop 0
	v_pk_mul_f32 v[166:167], v[166:167], s[10:11] op_sel_hi:[1,0]
	s_nop 0
	v_exp_f32_e32 v166, v166
	v_exp_f32_e32 v167, v167
	s_nop 0
	v_pk_add_f32 v[166:167], v[166:167], 1.0 op_sel_hi:[1,0]
	s_nop 0
	v_rcp_f32_e32 v166, v166
	v_rcp_f32_e32 v167, v167
	s_nop 0
	v_pk_fma_f32 v[166:167], v[194:195], v[166:167], v[132:133]
	s_nop 0
	s_nop 1
	v_log_f32_e32 v166, v166
	s_nop 0
	v_mul_f32_e32 v168, 0x3f317217, v166
	v_fma_f32 v168, v166, s3, -v168
	v_fmac_f32_e32 v168, 0x3377d1cf, v166
	v_fmac_f32_e32 v168, 0x3f317217, v166
	s_nop 1
	v_mov_b32_e32 v166, v168
	v_max_f32_e32 v168, 0xc2700000, v166
	s_nop 0
	v_log_f32_e32 v166, v167
	s_nop 0
	v_mul_f32_e32 v167, 0x3f317217, v166
	v_fma_f32 v167, v166, s3, -v167
	v_fmac_f32_e32 v167, 0x3377d1cf, v166
	v_fmac_f32_e32 v167, 0x3f317217, v166
	s_nop 1
	v_mov_b32_e32 v166, v167
	v_max_f32_e32 v182, 0xc2700000, v166
	v_pk_mul_f32 v[166:167], v[150:151], v[162:163] op_sel_hi:[1,0]
	s_nop 0
	v_pk_mul_f32 v[164:165], v[164:165], v[166:167]
	s_nop 0
	v_pk_mul_f32 v[164:165], v[164:165], s[10:11] op_sel_hi:[1,0]
	s_nop 0
	v_exp_f32_e32 v164, v164
	v_exp_f32_e32 v165, v165
	s_nop 0
	v_pk_add_f32 v[164:165], v[164:165], 1.0 op_sel_hi:[1,0]
	s_nop 0
	v_rcp_f32_e32 v164, v164
	v_rcp_f32_e32 v165, v165
	s_nop 0
	v_pk_fma_f32 v[164:165], v[206:207], v[164:165], v[134:135]
	s_nop 0
	s_nop 1
	v_log_f32_e32 v164, v164
	s_nop 0
	v_mul_f32_e32 v166, 0x3f317217, v164
	v_fma_f32 v166, v164, s3, -v166
	v_fmac_f32_e32 v166, 0x3377d1cf, v164
	v_fmac_f32_e32 v166, 0x3f317217, v164
	s_nop 1
	v_mov_b32_e32 v164, v166
	v_max_f32_e32 v167, 0xc2700000, v164
	v_cvt_pk_bf16_f32 v166, v168, v182
	v_log_f32_e32 v164, v165
	v_mad_i64_i32 v[168:169], s[0:1], v169, s81, v[204:205]
	v_mul_f32_e32 v165, 0x3f317217, v164
	v_fma_f32 v165, v164, s3, -v165
	v_fmac_f32_e32 v165, 0x3377d1cf, v164
	v_fmac_f32_e32 v165, 0x3f317217, v164
	s_nop 1
	v_mov_b32_e32 v164, v165
	v_max_f32_e32 v183, 0xc2700000, v164
	v_cvt_pk_bf16_f32 v164, v157, v159
	v_cvt_pk_bf16_f32 v165, v161, v163
	v_cvt_pk_bf16_f32 v167, v167, v183
	v_lshl_add_u64 v[182:183], v[168:169], 0, v[152:153]
	global_store_dwordx4 v[182:183], v[164:167], off
	ds_bpermute_b32 v164, v210, v208 offset:64
	v_cvt_f32_i32_e32 v169, v85
	v_cvt_f32_i32_e32 v168, v84
	v_cvt_f32_i32_e32 v167, v87
	v_cvt_f32_i32_e32 v166, v86
	s_waitcnt lgkmcnt(0)
; __device__ __forceinline__ unsigned cvt_pk_bf16(float lo, float hi) { f32x2_t v = {lo, hi}; bf16x2_t b = __builtin_convertvector(v, bf16x2_t); return __builtin_bit_cast(unsigned, b); }
; __device__ __forceinline__ float fast_rcp(float x) { return __builtin_amdgcn_rcpf(x); }
;     template <int KIND>
;     __device__ __forceinline__ void run(const f32x4 (&acc)[2][2][4][2], const Unit& u, int wr, int wc, int fr, int fq) const {
;     ...
;                 for (int m = 0; m < 4; ++m) { const int row = row0 + ai * HALF + m * 16; const float a = __shfl(ai ? sa_hi : sa_lo, 16 * m + fr);
;                     const f32x4 f0 = __builtin_convertvector(__builtin_bit_cast(i32x4, acc[ai][bj][m][0]), f32x4), f1 = __builtin_convertvector(__builtin_bit_cast(i32x4, acc[ai][bj][m][1]), f32x4);
;                     f32x2_t v[4] = {(f32x2_t){f0[0], f0[1]}, (f32x2_t){f0[2], f0[3]}, (f32x2_t){f1[0], f1[1]}, (f32x2_t){f1[2], f1[3]}};
; #pragma unroll
;                     for (int j = 0; j < 4; ++j) {
;                         v[j] = v[j] * (sc2[j] * (f32x2_t){a, a});
;                         if (KIND == 0 || KIND == 1 || KIND == 3) {
;                             const f32x2_t e = v[j] * (f32x2_t){-LOG2E, -LOG2E};
;                             const f32x2_t dn = (f32x2_t){__builtin_amdgcn_exp2f(e[0]), __builtin_amdgcn_exp2f(e[1])} + (f32x2_t){1.0f, 1.0f};
;                             const f32x2_t sg = (f32x2_t){fast_rcp(dn[0]), fast_rcp(dn[1])};
;                             if (KIND == 0) v[j] = v[j] * sg;
;                             else if (KIND == 3) v[j] = (v[j] * sg) * aux2[j];
;                             else { const f32x2_t f = __builtin_elementwise_fma((f32x2_t){1.0f, 1.0f} - aux2[j], sg, aux2[j]);
;                                 v[j] = (f32x2_t){fmaxf(__logf(f[0]), -60.0f), fmaxf(__logf(f[1]), -60.0f)}; }
;                         }
;                     }
;                     u32x4 w; w.x = cvt_pk_bf16(v[0][0], v[0][1]); w.y = cvt_pk_bf16(v[1][0], v[1][1]); w.z = cvt_pk_bf16(v[2][0], v[2][1]); w.w = cvt_pk_bf16(v[3][0], v[3][1]);
;                     *(u32x4*)(O + (size_t)row * NPROJ + col0 + bj * HALF) = w; }
	v_pk_mul_f32 v[198:199], v[188:189], v[164:165] op_sel_hi:[1,0]
	s_nop 0
	v_pk_mul_f32 v[196:197], v[196:197], v[198:199]
	v_cvt_f32_i32_e32 v199, v81
	v_pk_mul_f32 v[196:197], v[196:197], s[10:11] op_sel_hi:[1,0]
	v_cvt_f32_i32_e32 v198, v80
	v_exp_f32_e32 v196, v196
	v_exp_f32_e32 v197, v197
	s_nop 0
	v_pk_add_f32 v[196:197], v[196:197], 1.0 op_sel_hi:[1,0]
	s_nop 0
	v_rcp_f32_e32 v196, v196
	v_rcp_f32_e32 v197, v197
	s_nop 0
	v_pk_fma_f32 v[196:197], v[190:191], v[196:197], v[136:137]
	s_nop 0
	s_nop 1
	v_log_f32_e32 v157, v196
	s_nop 0
	v_mul_f32_e32 v159, 0x3f317217, v157
	v_fma_f32 v159, v157, s3, -v159
	v_fmac_f32_e32 v159, 0x3377d1cf, v157
	v_fmac_f32_e32 v159, 0x3f317217, v157
	s_nop 1
	v_mov_b32_e32 v157, v159
	v_max_f32_e32 v157, 0xc2700000, v157
	v_log_f32_e32 v159, v197
	v_pk_mul_f32 v[196:197], v[180:181], v[164:165] op_sel_hi:[1,0]
	v_pk_mul_f32 v[184:185], v[184:185], v[196:197]
	v_cvt_f32_i32_e32 v197, v83
	v_pk_mul_f32 v[184:185], v[184:185], s[10:11] op_sel_hi:[1,0]
	v_mul_f32_e32 v161, 0x3f317217, v159
	v_exp_f32_e32 v184, v184
	v_exp_f32_e32 v185, v185
	v_fma_f32 v161, v159, s3, -v161
	v_fmac_f32_e32 v161, 0x3377d1cf, v159
	v_fmac_f32_e32 v161, 0x3f317217, v159
	v_pk_add_f32 v[184:185], v[184:185], 1.0 op_sel_hi:[1,0]
	v_rcp_f32_e32 v184, v184
	v_rcp_f32_e32 v185, v185
	v_mov_b32_e32 v159, v161
	v_pk_fma_f32 v[184:185], v[192:193], v[184:185], v[138:139]
	v_max_f32_e32 v159, 0xc2700000, v159
	v_cvt_f32_i32_e32 v196, v82
	s_nop 0
	v_log_f32_e32 v161, v184
	s_nop 0
	v_mul_f32_e32 v163, 0x3f317217, v161
	v_fma_f32 v163, v161, s3, -v163
	v_fmac_f32_e32 v163, 0x3377d1cf, v161
	v_fmac_f32_e32 v163, 0x3f317217, v161
	s_nop 1
	v_mov_b32_e32 v161, v163
	v_max_f32_e32 v161, 0xc2700000, v161
	v_log_f32_e32 v163, v185
	s_nop 0
	v_mul_f32_e32 v165, 0x3f317217, v163
	v_fma_f32 v165, v163, s3, -v165
	v_fmac_f32_e32 v165, 0x3377d1cf, v163
	v_fmac_f32_e32 v165, 0x3f317217, v163
	s_nop 1
	v_mov_b32_e32 v163, v165
	v_pk_mul_f32 v[184:185], v[170:171], v[164:165] op_sel_hi:[1,0]
	v_pk_mul_f32 v[168:169], v[168:169], v[184:185]
	v_max_f32_e32 v163, 0xc2700000, v163
	v_pk_mul_f32 v[168:169], v[168:169], s[10:11] op_sel_hi:[1,0]
	s_nop 0
	v_exp_f32_e32 v168, v168
	v_exp_f32_e32 v169, v169
	s_nop 0
	v_pk_add_f32 v[168:169], v[168:169], 1.0 op_sel_hi:[1,0]
	s_nop 0
	v_rcp_f32_e32 v168, v168
	v_rcp_f32_e32 v169, v169
	s_nop 0
	v_pk_fma_f32 v[168:169], v[194:195], v[168:169], v[132:133]
	s_nop 0
	s_nop 1
	v_log_f32_e32 v165, v168
	s_nop 0
	v_mul_f32_e32 v168, 0x3f317217, v165
	v_fma_f32 v168, v165, s3, -v168
	v_fmac_f32_e32 v168, 0x3377d1cf, v165
	v_fmac_f32_e32 v168, 0x3f317217, v165
	s_nop 1
	v_mov_b32_e32 v165, v168
	v_max_f32_e32 v165, 0xc2700000, v165
	v_log_f32_e32 v168, v169
	s_nop 0
	v_mul_f32_e32 v169, 0x3f317217, v168
	v_fma_f32 v169, v168, s3, -v169
	v_fmac_f32_e32 v169, 0x3377d1cf, v168
	v_fmac_f32_e32 v169, 0x3f317217, v168
	s_nop 1
	v_mov_b32_e32 v168, v169
	v_max_f32_e32 v184, 0xc2700000, v168
	v_pk_mul_f32 v[168:169], v[150:151], v[164:165] op_sel_hi:[1,0]
	s_nop 0
	v_pk_mul_f32 v[166:167], v[166:167], v[168:169]
	s_nop 0
	v_pk_mul_f32 v[166:167], v[166:167], s[10:11] op_sel_hi:[1,0]
	s_nop 0
	v_exp_f32_e32 v166, v166
	v_exp_f32_e32 v167, v167
	s_nop 0
	v_pk_add_f32 v[166:167], v[166:167], 1.0 op_sel_hi:[1,0]
	s_nop 0
	v_rcp_f32_e32 v166, v166
	v_rcp_f32_e32 v167, v167
	s_nop 0
	v_pk_fma_f32 v[166:167], v[206:207], v[166:167], v[134:135]
	s_nop 0
	s_nop 1
	v_log_f32_e32 v166, v166
	s_nop 0
	v_mul_f32_e32 v168, 0x3f317217, v166
	v_fma_f32 v168, v166, s3, -v168
	v_fmac_f32_e32 v168, 0x3377d1cf, v166
	v_fmac_f32_e32 v168, 0x3f317217, v166
	s_nop 1
	v_mov_b32_e32 v166, v168
	v_max_f32_e32 v169, 0xc2700000, v166
	v_cvt_pk_bf16_f32 v168, v165, v184
	v_log_f32_e32 v166, v167
	s_nop 0
	v_mul_f32_e32 v167, 0x3f317217, v166
	v_fma_f32 v167, v166, s3, -v167
	v_fmac_f32_e32 v167, 0x3377d1cf, v166
	v_fmac_f32_e32 v167, 0x3f317217, v166
	s_nop 1
	v_mov_b32_e32 v166, v167
	v_max_f32_e32 v185, 0xc2700000, v166
	v_cvt_pk_bf16_f32 v169, v169, v185
	v_mad_i64_i32 v[184:185], s[0:1], v186, s81, v[204:205]
	v_cvt_pk_bf16_f32 v166, v157, v159
	v_cvt_pk_bf16_f32 v167, v161, v163
	v_lshl_add_u64 v[184:185], v[184:185], 0, v[152:153]
	global_store_dwordx4 v[184:185], v[166:169], off
	ds_bpermute_b32 v166, v210, v208 offset:128
	v_cvt_f32_i32_e32 v186, v76
	v_cvt_f32_i32_e32 v169, v79
	v_cvt_f32_i32_e32 v168, v78
	s_waitcnt lgkmcnt(0)
; __device__ __forceinline__ unsigned cvt_pk_bf16(float lo, float hi) { f32x2_t v = {lo, hi}; bf16x2_t b = __builtin_convertvector(v, bf16x2_t); return __builtin_bit_cast(unsigned, b); }
; __device__ __forceinline__ float fast_rcp(float x) { return __builtin_amdgcn_rcpf(x); }
;     template <int KIND>
;     __device__ __forceinline__ void run(const f32x4 (&acc)[2][2][4][2], const Unit& u, int wr, int wc, int fr, int fq) const {
;     ...
;                 for (int m = 0; m < 4; ++m) { const int row = row0 + ai * HALF + m * 16; const float a = __shfl(ai ? sa_hi : sa_lo, 16 * m + fr);
;                     const f32x4 f0 = __builtin_convertvector(__builtin_bit_cast(i32x4, acc[ai][bj][m][0]), f32x4), f1 = __builtin_convertvector(__builtin_bit_cast(i32x4, acc[ai][bj][m][1]), f32x4);
;                     f32x2_t v[4] = {(f32x2_t){f0[0], f0[1]}, (f32x2_t){f0[2], f0[3]}, (f32x2_t){f1[0], f1[1]}, (f32x2_t){f1[2], f1[3]}};
; #pragma unroll
;                     for (int j = 0; j < 4; ++j) {
;                         v[j] = v[j] * (sc2[j] * (f32x2_t){a, a});
;                         if (KIND == 0 || KIND == 1 || KIND == 3) {
;                             const f32x2_t e = v[j] * (f32x2_t){-LOG2E, -LOG2E};
;                             const f32x2_t dn = (f32x2_t){__builtin_amdgcn_exp2f(e[0]), __builtin_amdgcn_exp2f(e[1])} + (f32x2_t){1.0f, 1.0f};
;                             const f32x2_t sg = (f32x2_t){fast_rcp(dn[0]), fast_rcp(dn[1])};
;                             if (KIND == 0) v[j] = v[j] * sg;
;                             else if (KIND == 3) v[j] = (v[j] * sg) * aux2[j];
;                             else { const f32x2_t f = __builtin_elementwise_fma((f32x2_t){1.0f, 1.0f} - aux2[j], sg, aux2[j]);
;                                 v[j] = (f32x2_t){fmaxf(__logf(f[0]), -60.0f), fmaxf(__logf(f[1]), -60.0f)}; }
;                         }
;                     }
;                     u32x4 w; w.x = cvt_pk_bf16(v[0][0], v[0][1]); w.y = cvt_pk_bf16(v[1][0], v[1][1]); w.z = cvt_pk_bf16(v[2][0], v[2][1]); w.w = cvt_pk_bf16(v[3][0], v[3][1]);
;                     *(u32x4*)(O + (size_t)row * NPROJ + col0 + bj * HALF) = w; }
	v_pk_mul_f32 v[200:201], v[188:189], v[166:167] op_sel_hi:[1,0]
	s_nop 0
	v_pk_mul_f32 v[198:199], v[198:199], v[200:201]
	s_nop 0
	v_pk_mul_f32 v[198:199], v[198:199], s[10:11] op_sel_hi:[1,0]
	s_nop 0
	v_exp_f32_e32 v198, v198
	v_exp_f32_e32 v199, v199
	s_nop 0
	v_pk_add_f32 v[198:199], v[198:199], 1.0 op_sel_hi:[1,0]
	s_nop 0
	v_rcp_f32_e32 v198, v198
	v_rcp_f32_e32 v199, v199
	s_nop 0
	v_pk_fma_f32 v[198:199], v[190:191], v[198:199], v[136:137]
	s_nop 0
	s_nop 1
	v_log_f32_e32 v157, v198
	s_nop 0
	v_mul_f32_e32 v159, 0x3f317217, v157
	v_fma_f32 v159, v157, s3, -v159
	v_fmac_f32_e32 v159, 0x3377d1cf, v157
	v_fmac_f32_e32 v159, 0x3f317217, v157
	s_nop 1
	v_mov_b32_e32 v157, v159
	v_max_f32_e32 v157, 0xc2700000, v157
	v_log_f32_e32 v159, v199
	v_pk_mul_f32 v[198:199], v[180:181], v[166:167] op_sel_hi:[1,0]
	v_pk_mul_f32 v[196:197], v[196:197], v[198:199]
	v_mul_f32_e32 v161, 0x3f317217, v159
	v_pk_mul_f32 v[196:197], v[196:197], s[10:11] op_sel_hi:[1,0]
	v_fma_f32 v161, v159, s3, -v161
	v_exp_f32_e32 v196, v196
	v_exp_f32_e32 v197, v197
	v_fmac_f32_e32 v161, 0x3377d1cf, v159
	v_fmac_f32_e32 v161, 0x3f317217, v159
	v_pk_add_f32 v[196:197], v[196:197], 1.0 op_sel_hi:[1,0]
	s_nop 0
	v_rcp_f32_e32 v196, v196
	v_rcp_f32_e32 v197, v197
	v_mov_b32_e32 v159, v161
	v_pk_fma_f32 v[196:197], v[192:193], v[196:197], v[138:139]
	v_max_f32_e32 v159, 0xc2700000, v159
	s_nop 1
	v_log_f32_e32 v161, v196
	s_nop 0
	v_mul_f32_e32 v163, 0x3f317217, v161
	v_fma_f32 v163, v161, s3, -v163
	v_fmac_f32_e32 v163, 0x3377d1cf, v161
	v_fmac_f32_e32 v163, 0x3f317217, v161
	s_nop 1
	v_mov_b32_e32 v161, v163
	v_max_f32_e32 v161, 0xc2700000, v161
	v_log_f32_e32 v163, v197
	v_pk_mul_f32 v[196:197], v[170:171], v[166:167] op_sel_hi:[1,0]
	v_pk_mul_f32 v[186:187], v[186:187], v[196:197]
	v_cvt_pk_bf16_f32 v196, v157, v159
	v_pk_mul_f32 v[186:187], v[186:187], s[10:11] op_sel_hi:[1,0]
	v_mul_f32_e32 v165, 0x3f317217, v163
	v_exp_f32_e32 v186, v186
	v_exp_f32_e32 v187, v187
	v_fma_f32 v165, v163, s3, -v165
	v_fmac_f32_e32 v165, 0x3377d1cf, v163
	v_fmac_f32_e32 v165, 0x3f317217, v163
	v_pk_add_f32 v[186:187], v[186:187], 1.0 op_sel_hi:[1,0]
	v_rcp_f32_e32 v186, v186
	v_rcp_f32_e32 v187, v187
	v_mov_b32_e32 v163, v165
	v_pk_fma_f32 v[186:187], v[194:195], v[186:187], v[132:133]
	v_max_f32_e32 v163, 0xc2700000, v163
	v_cvt_pk_bf16_f32 v197, v161, v163
	s_nop 0
	v_log_f32_e32 v165, v186
	s_nop 0
	v_mul_f32_e32 v167, 0x3f317217, v165
	v_fma_f32 v167, v165, s3, -v167
	v_fmac_f32_e32 v167, 0x3377d1cf, v165
	v_fmac_f32_e32 v167, 0x3f317217, v165
	s_nop 1
	v_mov_b32_e32 v165, v167
	v_max_f32_e32 v165, 0xc2700000, v165
	v_log_f32_e32 v167, v187
	s_nop 0
	v_mul_f32_e32 v186, 0x3f317217, v167
	v_fma_f32 v186, v167, s3, -v186
	v_fmac_f32_e32 v186, 0x3377d1cf, v167
	v_fmac_f32_e32 v186, 0x3f317217, v167
	s_nop 1
	v_mov_b32_e32 v167, v186
	v_max_f32_e32 v167, 0xc2700000, v167
	v_pk_mul_f32 v[186:187], v[150:151], v[166:167] op_sel_hi:[1,0]
	v_cvt_pk_bf16_f32 v198, v165, v167
	v_pk_mul_f32 v[168:169], v[168:169], v[186:187]
	s_nop 0
	v_pk_mul_f32 v[168:169], v[168:169], s[10:11] op_sel_hi:[1,0]
	s_nop 0
	v_exp_f32_e32 v168, v168
	v_exp_f32_e32 v169, v169
	s_nop 0
	v_pk_add_f32 v[168:169], v[168:169], 1.0 op_sel_hi:[1,0]
	s_nop 0
	v_rcp_f32_e32 v168, v168
	v_rcp_f32_e32 v169, v169
	s_nop 0
	v_pk_fma_f32 v[168:169], v[206:207], v[168:169], v[134:135]
	s_nop 0
	s_nop 1
	v_log_f32_e32 v168, v168
	s_nop 0
	v_mul_f32_e32 v186, 0x3f317217, v168
	v_fma_f32 v186, v168, s3, -v186
	v_fmac_f32_e32 v186, 0x3377d1cf, v168
	v_fmac_f32_e32 v186, 0x3f317217, v168
	s_nop 1
	v_mov_b32_e32 v168, v186
	v_max_f32_e32 v168, 0xc2700000, v168
	v_log_f32_e32 v169, v169
	s_nop 0
	v_mul_f32_e32 v186, 0x3f317217, v169
	v_fma_f32 v186, v169, s3, -v186
	v_fmac_f32_e32 v186, 0x3377d1cf, v169
	v_fmac_f32_e32 v186, 0x3f317217, v169
	s_nop 1
	v_mov_b32_e32 v169, v186
	v_max_f32_e32 v169, 0xc2700000, v169
	v_cvt_pk_bf16_f32 v199, v168, v169
	v_mad_i64_i32 v[168:169], s[0:1], v211, s81, v[204:205]
	v_lshl_add_u64 v[186:187], v[168:169], 0, v[152:153]
	ds_bpermute_b32 v168, v210, v208 offset:192
	global_store_dwordx4 v[186:187], v[196:199], off
	v_cvt_f32_i32_e32 v211, v69
	v_cvt_f32_i32_e32 v210, v68
	v_cvt_f32_i32_e32 v199, v73
	v_cvt_f32_i32_e32 v198, v72
	s_waitcnt lgkmcnt(0)
; __device__ __forceinline__ unsigned cvt_pk_bf16(float lo, float hi) { f32x2_t v = {lo, hi}; bf16x2_t b = __builtin_convertvector(v, bf16x2_t); return __builtin_bit_cast(unsigned, b); }
; __device__ __forceinline__ float fast_rcp(float x) { return __builtin_amdgcn_rcpf(x); }
;     template <int KIND>
;     __device__ __forceinline__ void run(const f32x4 (&acc)[2][2][4][2], const Unit& u, int wr, int wc, int fr, int fq) const {
;     ...
;                 for (int m = 0; m < 4; ++m) { const int row = row0 + ai * HALF + m * 16; const float a = __shfl(ai ? sa_hi : sa_lo, 16 * m + fr);
;                     const f32x4 f0 = __builtin_convertvector(__builtin_bit_cast(i32x4, acc[ai][bj][m][0]), f32x4), f1 = __builtin_convertvector(__builtin_bit_cast(i32x4, acc[ai][bj][m][1]), f32x4);
;                     f32x2_t v[4] = {(f32x2_t){f0[0], f0[1]}, (f32x2_t){f0[2], f0[3]}, (f32x2_t){f1[0], f1[1]}, (f32x2_t){f1[2], f1[3]}};
; #pragma unroll
;                     for (int j = 0; j < 4; ++j) {
;                         v[j] = v[j] * (sc2[j] * (f32x2_t){a, a});
;                         if (KIND == 0 || KIND == 1 || KIND == 3) {
;                             const f32x2_t e = v[j] * (f32x2_t){-LOG2E, -LOG2E};
;                             const f32x2_t dn = (f32x2_t){__builtin_amdgcn_exp2f(e[0]), __builtin_amdgcn_exp2f(e[1])} + (f32x2_t){1.0f, 1.0f};
;                             const f32x2_t sg = (f32x2_t){fast_rcp(dn[0]), fast_rcp(dn[1])};
;                             if (KIND == 0) v[j] = v[j] * sg;
;                             else if (KIND == 3) v[j] = (v[j] * sg) * aux2[j];
;                             else { const f32x2_t f = __builtin_elementwise_fma((f32x2_t){1.0f, 1.0f} - aux2[j], sg, aux2[j]);
;                                 v[j] = (f32x2_t){fmaxf(__logf(f[0]), -60.0f), fmaxf(__logf(f[1]), -60.0f)}; }
;                         }
;                     }
;                     u32x4 w; w.x = cvt_pk_bf16(v[0][0], v[0][1]); w.y = cvt_pk_bf16(v[1][0], v[1][1]); w.z = cvt_pk_bf16(v[2][0], v[2][1]); w.w = cvt_pk_bf16(v[3][0], v[3][1]);
;                     *(u32x4*)(O + (size_t)row * NPROJ + col0 + bj * HALF) = w; }
	v_pk_mul_f32 v[188:189], v[188:189], v[168:169] op_sel_hi:[1,0]
	v_cvt_f32_i32_e32 v197, v75
	v_cvt_f32_i32_e32 v196, v74
	v_pk_mul_f32 v[188:189], v[198:199], v[188:189]
	v_cvt_f32_i32_e32 v208, v70
	v_pk_mul_f32 v[188:189], v[188:189], s[10:11] op_sel_hi:[1,0]
	v_cvt_f32_i32_e32 v199, v55
	v_exp_f32_e32 v188, v188
	v_exp_f32_e32 v189, v189
	v_cvt_f32_i32_e32 v198, v54
	v_pk_add_f32 v[188:189], v[188:189], 1.0 op_sel_hi:[1,0]
	s_nop 0
	v_rcp_f32_e32 v188, v188
	v_rcp_f32_e32 v189, v189
	s_nop 0
	v_pk_fma_f32 v[136:137], v[190:191], v[188:189], v[136:137]
	s_nop 0
	s_nop 1
	v_log_f32_e32 v136, v136
	s_nop 0
	v_mul_f32_e32 v157, 0x3f317217, v136
	v_fma_f32 v157, v136, s3, -v157
	v_fmac_f32_e32 v157, 0x3377d1cf, v136
	v_fmac_f32_e32 v157, 0x3f317217, v136
	s_nop 1
	v_mov_b32_e32 v136, v157
	v_max_f32_e32 v157, 0xc2700000, v136
	s_nop 0
	v_log_f32_e32 v136, v137
	s_nop 0
	v_mul_f32_e32 v137, 0x3f317217, v136
	v_fma_f32 v137, v136, s3, -v137
	v_fmac_f32_e32 v137, 0x3377d1cf, v136
	v_fmac_f32_e32 v137, 0x3f317217, v136
	s_nop 1
	v_mov_b32_e32 v136, v137
	v_max_f32_e32 v159, 0xc2700000, v136
	v_pk_mul_f32 v[136:137], v[180:181], v[168:169] op_sel_hi:[1,0]
	v_cvt_f32_i32_e32 v181, v63
	v_pk_mul_f32 v[136:137], v[196:197], v[136:137]
	v_cvt_f32_i32_e32 v180, v62
	v_pk_mul_f32 v[136:137], v[136:137], s[10:11] op_sel_hi:[1,0]
	s_nop 0
	v_exp_f32_e32 v136, v136
	v_exp_f32_e32 v137, v137
	s_nop 0
	v_pk_add_f32 v[136:137], v[136:137], 1.0 op_sel_hi:[1,0]
	s_nop 0
	v_rcp_f32_e32 v136, v136
	v_rcp_f32_e32 v137, v137
	s_nop 0
	v_pk_fma_f32 v[136:137], v[192:193], v[136:137], v[138:139]
	s_nop 0
	s_nop 1
	v_log_f32_e32 v136, v136
	s_nop 0
	v_mul_f32_e32 v138, 0x3f317217, v136
	v_fma_f32 v138, v136, s3, -v138
	v_fmac_f32_e32 v138, 0x3377d1cf, v136
	v_fmac_f32_e32 v138, 0x3f317217, v136
	s_nop 1
	v_mov_b32_e32 v136, v138
	v_max_f32_e32 v138, 0xc2700000, v136
	s_nop 0
	v_log_f32_e32 v136, v137
	s_nop 0
	v_mul_f32_e32 v137, 0x3f317217, v136
	v_fma_f32 v137, v136, s3, -v137
	v_fmac_f32_e32 v137, 0x3377d1cf, v136
	v_fmac_f32_e32 v137, 0x3f317217, v136
	s_nop 1
	v_mov_b32_e32 v136, v137
	v_max_f32_e32 v139, 0xc2700000, v136
	v_pk_mul_f32 v[136:137], v[170:171], v[168:169] op_sel_hi:[1,0]
	s_nop 0
	v_pk_mul_f32 v[136:137], v[210:211], v[136:137]
	s_nop 0
	v_pk_mul_f32 v[136:137], v[136:137], s[10:11] op_sel_hi:[1,0]
	s_nop 0
	v_exp_f32_e32 v136, v136
	v_exp_f32_e32 v137, v137
	s_nop 0
	v_pk_add_f32 v[136:137], v[136:137], 1.0 op_sel_hi:[1,0]
	s_nop 0
	v_rcp_f32_e32 v136, v136
	v_rcp_f32_e32 v137, v137
	s_nop 0
	v_pk_fma_f32 v[132:133], v[194:195], v[136:137], v[132:133]
	s_nop 0
	s_nop 1
	v_log_f32_e32 v132, v132
	s_nop 0
	v_mul_f32_e32 v136, 0x3f317217, v132
	v_fma_f32 v136, v132, s3, -v136
	v_fmac_f32_e32 v136, 0x3377d1cf, v132
	v_fmac_f32_e32 v136, 0x3f317217, v132
	s_nop 1
	v_mov_b32_e32 v132, v136
	v_max_f32_e32 v136, 0xc2700000, v132
	s_nop 0
	v_log_f32_e32 v132, v133
	s_nop 0
	v_mul_f32_e32 v133, 0x3f317217, v132
	v_fma_f32 v133, v132, s3, -v133
	v_fmac_f32_e32 v133, 0x3377d1cf, v132
	v_fmac_f32_e32 v133, 0x3f317217, v132
	s_nop 1
	v_mov_b32_e32 v132, v133
	v_max_f32_e32 v137, 0xc2700000, v132
	v_pk_mul_f32 v[132:133], v[150:151], v[168:169] op_sel_hi:[1,0]
	s_nop 0
	v_pk_mul_f32 v[132:133], v[208:209], v[132:133]
	s_nop 0
	v_pk_mul_f32 v[132:133], v[132:133], s[10:11] op_sel_hi:[1,0]
	s_nop 0
	v_exp_f32_e32 v132, v132
	v_exp_f32_e32 v133, v133
	s_nop 0
	v_pk_add_f32 v[132:133], v[132:133], 1.0 op_sel_hi:[1,0]
	s_nop 0
	v_rcp_f32_e32 v132, v132
	v_rcp_f32_e32 v133, v133
	s_nop 0
	v_pk_fma_f32 v[132:133], v[206:207], v[132:133], v[134:135]
	s_nop 0
	s_nop 1
	v_log_f32_e32 v132, v132
	s_nop 0
	v_mul_f32_e32 v134, 0x3f317217, v132
	v_fma_f32 v134, v132, s3, -v134
	v_fmac_f32_e32 v134, 0x3377d1cf, v132
	v_fmac_f32_e32 v134, 0x3f317217, v132
	s_nop 1
	v_mov_b32_e32 v132, v134
	v_max_f32_e32 v135, 0xc2700000, v132
	v_cvt_pk_bf16_f32 v134, v136, v137
	v_log_f32_e32 v132, v133
	v_mad_i64_i32 v[136:137], s[0:1], v234, s81, v[204:205]
	v_lshl_add_u64 v[136:137], v[136:137], 0, v[152:153]
	v_mul_f32_e32 v133, 0x3f317217, v132
	v_fma_f32 v133, v132, s3, -v133
	v_fmac_f32_e32 v133, 0x3377d1cf, v132
	v_fmac_f32_e32 v133, 0x3f317217, v132
	s_nop 1
	v_mov_b32_e32 v132, v133
	v_max_f32_e32 v150, 0xc2700000, v132
	v_cvt_pk_bf16_f32 v132, v157, v159
	v_cvt_pk_bf16_f32 v133, v138, v139
	v_cvt_pk_bf16_f32 v135, v135, v150
	global_store_dwordx4 v[136:137], v[132:135], off
	s_waitcnt vmcnt(8)
;     template <int KIND>
;     __device__ __forceinline__ void run(const f32x4 (&acc)[2][2][4][2], const Unit& u, int wr, int wc, int fr, int fq) const {
;     ...
;         for (int bj = 0; bj < 2; ++bj) {
;             f32x2_t sc2[4], aux2[4];
; #pragma unroll
;             for (int j = 0; j < 4; ++j) {
;                 const float k0 = (KIND == 4) ? (0.125f * LOG2E / 127.0f) : (1.0f / 127.0f);
;                 sc2[j] = (f32x2_t){wmax[col0 + bj * HALF + 2 * j] * k0, wmax[col0 + bj * HALF + 2 * j + 1] * k0};
;                 if (KIND == 1) aux2[j] = (f32x2_t){lb[col0 - C_HG + bj * HALF + 2 * j], lb[col0 - C_HG + bj * HALF + 2 * j + 1]};
;                 else if (KIND == 3) aux2[j] = (f32x2_t){gain[col0 - C_HGATE + bj * HALF + 2 * j], gain[col0 - C_HGATE + bj * HALF + 2 * j + 1]};
;                 else aux2[j] = (f32x2_t){0.f, 0.f};
;             }
; #pragma unroll
;             for (int ai = 0; ai < 2; ++ai)
; #pragma unroll
;                 for (int m = 0; m < 4; ++m) { const int row = row0 + ai * HALF + m * 16; const float a = __shfl(ai ? sa_hi : sa_lo, 16 * m + fr);
;                     const f32x4 f0 = __builtin_convertvector(__builtin_bit_cast(i32x4, acc[ai][bj][m][0]), f32x4), f1 = __builtin_convertvector(__builtin_bit_cast(i32x4, acc[ai][bj][m][1]), f32x4);
;                     f32x2_t v[4] = {(f32x2_t){f0[0], f0[1]}, (f32x2_t){f0[2], f0[3]}, (f32x2_t){f1[0], f1[1]}, (f32x2_t){f1[2], f1[3]}};
; #pragma unroll
;                     for (int j = 0; j < 4; ++j) {
;                         v[j] = v[j] * (sc2[j] * (f32x2_t){a, a});
;                         if (KIND == 0 || KIND == 1 || KIND == 3) {
;                             const f32x2_t e = v[j] * (f32x2_t){-LOG2E, -LOG2E};
;                             const f32x2_t dn = (f32x2_t){__builtin_amdgcn_exp2f(e[0]), __builtin_amdgcn_exp2f(e[1])} + (f32x2_t){1.0f, 1.0f};
;                             const f32x2_t sg = (f32x2_t){fast_rcp(dn[0]), fast_rcp(dn[1])};
;                             if (KIND == 0) v[j] = v[j] * sg;
;                             else if (KIND == 3) v[j] = (v[j] * sg) * aux2[j];
;                             else { const f32x2_t f = __builtin_elementwise_fma((f32x2_t){1.0f, 1.0f} - aux2[j], sg, aux2[j]);
;                                 v[j] = (f32x2_t){fmaxf(__logf(f[0]), -60.0f), fmaxf(__logf(f[1]), -60.0f)}; }
;                         }
;                     }
	s_nop 0
	v_mov_b32_e32 v188, v236
	v_mov_b32_e32 v189, v237
	v_mov_b32_e32 v190, v238
	v_mov_b32_e32 v191, v239
	v_mov_b32_e32 v192, v240
	v_mov_b32_e32 v193, v241
	v_mov_b32_e32 v194, v242
	v_mov_b32_e32 v195, v243
	v_mov_b32_e32 v132, v128
	v_mov_b32_e32 v133, v129
	v_mov_b32_e32 v134, v130
	v_mov_b32_e32 v135, v131
	v_mov_b32_e32 v136, v244
	v_mov_b32_e32 v137, v245
	v_mov_b32_e32 v138, v246
	v_mov_b32_e32 v139, v247
	v_mad_i64_i32 v[150:151], s[0:1], v234, s81, 0
	v_pk_mul_f32 v[152:153], v[188:189], s[8:9] op_sel_hi:[1,0]
	v_pk_mul_f32 v[170:171], v[192:193], s[8:9] op_sel_hi:[1,0]
	v_pk_mul_f32 v[154:155], v[194:195], s[8:9] op_sel_hi:[1,0]
	v_pk_mul_f32 v[194:195], v[66:67], v[170:171] op_sel_hi:[0,1]
	v_pk_mul_f32 v[180:181], v[180:181], v[194:195]
	v_cvt_f32_i32_e32 v189, v65
	v_pk_mul_f32 v[180:181], v[180:181], s[10:11] op_sel_hi:[1,0]
	v_cvt_f32_i32_e32 v188, v64
	v_exp_f32_e32 v180, v180
	v_exp_f32_e32 v181, v181
	v_pk_mul_f32 v[148:149], v[190:191], s[8:9] op_sel_hi:[1,0]
	v_cvt_f32_i32_e32 v191, v59
	v_cvt_f32_i32_e32 v190, v58
	v_pk_add_f32 v[180:181], v[180:181], 1.0 op_sel_hi:[1,0]
	v_cvt_f32_i32_e32 v193, v61
	v_rcp_f32_e32 v194, v180
	v_rcp_f32_e32 v195, v181
	v_pk_add_f32 v[180:181], v[136:137], 1.0 op_sel_hi:[1,0] neg_lo:[1,0] neg_hi:[1,0]
	v_cvt_f32_i32_e32 v192, v60
	v_pk_fma_f32 v[194:195], v[180:181], v[194:195], v[136:137]
	s_nop 0
	s_nop 1
	v_log_f32_e32 v157, v194
	s_nop 0
	v_mul_f32_e32 v159, 0x3f317217, v157
	v_fma_f32 v159, v157, s3, -v159
	v_fmac_f32_e32 v159, 0x3377d1cf, v157
	v_fmac_f32_e32 v159, 0x3f317217, v157
	s_nop 1
	v_mov_b32_e32 v157, v159
	v_max_f32_e32 v157, 0xc2700000, v157
	v_log_f32_e32 v159, v195
	v_pk_mul_f32 v[194:195], v[66:67], v[154:155] op_sel_hi:[0,1]
	v_pk_mul_f32 v[188:189], v[188:189], v[194:195]
	v_pk_mul_f32 v[188:189], v[188:189], s[10:11] op_sel_hi:[1,0]
	v_pk_mul_f32 v[200:201], v[156:157], v[170:171] op_sel_hi:[0,1]
	v_exp_f32_e32 v188, v188
	v_exp_f32_e32 v189, v189
	v_mul_f32_e32 v161, 0x3f317217, v159
	v_fma_f32 v161, v159, s3, -v161
	v_fmac_f32_e32 v161, 0x3377d1cf, v159
	v_pk_add_f32 v[188:189], v[188:189], 1.0 op_sel_hi:[1,0]
	v_fmac_f32_e32 v161, 0x3f317217, v159
	v_rcp_f32_e32 v194, v188
	v_rcp_f32_e32 v195, v189
	v_pk_add_f32 v[188:189], v[138:139], 1.0 op_sel_hi:[1,0] neg_lo:[1,0] neg_hi:[1,0]
	v_pk_mul_f32 v[198:199], v[198:199], v[200:201]
	v_pk_fma_f32 v[194:195], v[188:189], v[194:195], v[138:139]
	v_mov_b32_e32 v159, v161
	v_pk_mul_f32 v[198:199], v[198:199], s[10:11] op_sel_hi:[1,0]
	v_log_f32_e32 v161, v194
	v_exp_f32_e32 v198, v198
	v_exp_f32_e32 v199, v199
	v_max_f32_e32 v159, 0xc2700000, v159
	v_mul_f32_e32 v163, 0x3f317217, v161
	v_fma_f32 v163, v161, s3, -v163
	v_fmac_f32_e32 v163, 0x3377d1cf, v161
	v_fmac_f32_e32 v163, 0x3f317217, v161
	v_pk_add_f32 v[198:199], v[198:199], 1.0 op_sel_hi:[1,0]
	s_nop 0
	v_mov_b32_e32 v161, v163
	v_rcp_f32_e32 v198, v198
	v_log_f32_e32 v163, v195
	v_pk_mul_f32 v[194:195], v[66:67], v[152:153] op_sel_hi:[0,1]
	v_pk_mul_f32 v[190:191], v[190:191], v[194:195]
	v_pk_mul_f32 v[190:191], v[190:191], s[10:11] op_sel_hi:[1,0]
	v_rcp_f32_e32 v199, v199
	v_exp_f32_e32 v190, v190
	v_exp_f32_e32 v191, v191
	v_mul_f32_e32 v165, 0x3f317217, v163
	v_fma_f32 v165, v163, s3, -v165
	v_fmac_f32_e32 v165, 0x3377d1cf, v163
	v_pk_add_f32 v[190:191], v[190:191], 1.0 op_sel_hi:[1,0]
	v_fmac_f32_e32 v165, 0x3f317217, v163
	v_rcp_f32_e32 v194, v190
	v_rcp_f32_e32 v195, v191
	v_pk_add_f32 v[190:191], v[132:133], 1.0 op_sel_hi:[1,0] neg_lo:[1,0] neg_hi:[1,0]
	v_pk_fma_f32 v[198:199], v[180:181], v[198:199], v[136:137]
	v_pk_fma_f32 v[194:195], v[190:191], v[194:195], v[132:133]
	v_mov_b32_e32 v163, v165
	v_max_f32_e32 v161, 0xc2700000, v161
	v_log_f32_e32 v165, v194
	v_max_f32_e32 v163, 0xc2700000, v163
	v_mul_f32_e32 v167, 0x3f317217, v165
	v_fma_f32 v167, v165, s3, -v167
	v_fmac_f32_e32 v167, 0x3377d1cf, v165
	v_fmac_f32_e32 v167, 0x3f317217, v165
	s_nop 1
	v_mov_b32_e32 v165, v167
	v_max_f32_e32 v165, 0xc2700000, v165
	v_log_f32_e32 v167, v195
	v_pk_mul_f32 v[194:195], v[66:67], v[148:149] op_sel_hi:[0,1]
	v_pk_mul_f32 v[192:193], v[192:193], v[194:195]
	v_pk_mul_f32 v[192:193], v[192:193], s[10:11] op_sel_hi:[1,0]
	v_mul_f32_e32 v169, 0x3f317217, v167
	v_exp_f32_e32 v192, v192
	v_exp_f32_e32 v193, v193
	v_fma_f32 v169, v167, s3, -v169
	v_fmac_f32_e32 v169, 0x3377d1cf, v167
	v_fmac_f32_e32 v169, 0x3f317217, v167
	v_pk_add_f32 v[192:193], v[192:193], 1.0 op_sel_hi:[1,0]
	v_rcp_f32_e32 v194, v192
	v_rcp_f32_e32 v195, v193
	v_pk_add_f32 v[192:193], v[134:135], 1.0 op_sel_hi:[1,0] neg_lo:[1,0] neg_hi:[1,0]
	v_mov_b32_e32 v167, v169
	v_pk_fma_f32 v[194:195], v[192:193], v[194:195], v[134:135]
	v_max_f32_e32 v167, 0xc2700000, v167
	v_cvt_pk_bf16_f32 v196, v165, v167
	v_log_f32_e32 v66, v194
	s_nop 0
	v_mul_f32_e32 v169, 0x3f317217, v66
	v_fma_f32 v169, v66, s3, -v169
	v_fmac_f32_e32 v169, 0x3377d1cf, v66
	v_fmac_f32_e32 v169, 0x3f317217, v66
	s_nop 1
	v_mov_b32_e32 v66, v169
	v_max_f32_e32 v66, 0xc2700000, v66
	v_log_f32_e32 v169, v195
	v_cvt_pk_bf16_f32 v195, v161, v163
	v_mul_f32_e32 v194, 0x3f317217, v169
	v_fma_f32 v194, v169, s3, -v194
	v_fmac_f32_e32 v194, 0x3377d1cf, v169
	v_fmac_f32_e32 v194, 0x3f317217, v169
	s_nop 1
	v_mov_b32_e32 v169, v194
	v_max_f32_e32 v169, 0xc2700000, v169
	v_cvt_pk_bf16_f32 v197, v66, v169
	v_cvt_pk_bf16_f32 v194, v157, v159
	v_log_f32_e32 v66, v198
	global_store_dwordx4 v[172:173], v[194:197], off offset:256
	v_cvt_f32_i32_e32 v173, v53
	v_cvt_f32_i32_e32 v172, v52
	v_mul_f32_e32 v157, 0x3f317217, v66
	v_fma_f32 v157, v66, s3, -v157
	v_fmac_f32_e32 v157, 0x3377d1cf, v66
	v_fmac_f32_e32 v157, 0x3f317217, v66
; __device__ __forceinline__ unsigned cvt_pk_bf16(float lo, float hi) { f32x2_t v = {lo, hi}; bf16x2_t b = __builtin_convertvector(v, bf16x2_t); return __builtin_bit_cast(unsigned, b); }
; __device__ __forceinline__ float fast_rcp(float x) { return __builtin_amdgcn_rcpf(x); }
;     template <int KIND>
;     __device__ __forceinline__ void run(const f32x4 (&acc)[2][2][4][2], const Unit& u, int wr, int wc, int fr, int fq) const {
;     ...
;             for (int ai = 0; ai < 2; ++ai)
; #pragma unroll
;                 for (int m = 0; m < 4; ++m) { const int row = row0 + ai * HALF + m * 16; const float a = __shfl(ai ? sa_hi : sa_lo, 16 * m + fr);
;                     const f32x4 f0 = __builtin_convertvector(__builtin_bit_cast(i32x4, acc[ai][bj][m][0]), f32x4), f1 = __builtin_convertvector(__builtin_bit_cast(i32x4, acc[ai][bj][m][1]), f32x4);
;                     f32x2_t v[4] = {(f32x2_t){f0[0], f0[1]}, (f32x2_t){f0[2], f0[3]}, (f32x2_t){f1[0], f1[1]}, (f32x2_t){f1[2], f1[3]}};
; #pragma unroll
;                     for (int j = 0; j < 4; ++j) {
;                         v[j] = v[j] * (sc2[j] * (f32x2_t){a, a});
;                         if (KIND == 0 || KIND == 1 || KIND == 3) {
;                             const f32x2_t e = v[j] * (f32x2_t){-LOG2E, -LOG2E};
;                             const f32x2_t dn = (f32x2_t){__builtin_amdgcn_exp2f(e[0]), __builtin_amdgcn_exp2f(e[1])} + (f32x2_t){1.0f, 1.0f};
;                             const f32x2_t sg = (f32x2_t){fast_rcp(dn[0]), fast_rcp(dn[1])};
;                             if (KIND == 0) v[j] = v[j] * sg;
;                             else if (KIND == 3) v[j] = (v[j] * sg) * aux2[j];
;                             else { const f32x2_t f = __builtin_elementwise_fma((f32x2_t){1.0f, 1.0f} - aux2[j], sg, aux2[j]);
;                                 v[j] = (f32x2_t){fmaxf(__logf(f[0]), -60.0f), fmaxf(__logf(f[1]), -60.0f)}; }
;                         }
;                     }
;                     u32x4 w; w.x = cvt_pk_bf16(v[0][0], v[0][1]); w.y = cvt_pk_bf16(v[1][0], v[1][1]); w.z = cvt_pk_bf16(v[2][0], v[2][1]); w.w = cvt_pk_bf16(v[3][0], v[3][1]);
;                     *(u32x4*)(O + (size_t)row * NPROJ + col0 + bj * HALF) = w; }
	v_cvt_f32_i32_e32 v197, v57
	v_cvt_f32_i32_e32 v196, v56
	v_mov_b32_e32 v66, v157
	v_cvt_f32_i32_e32 v195, v51
	v_log_f32_e32 v157, v199
	v_cvt_f32_i32_e32 v194, v50
	v_max_f32_e32 v66, 0xc2700000, v66
	v_mul_f32_e32 v159, 0x3f317217, v157
	v_fma_f32 v159, v157, s3, -v159
	v_fmac_f32_e32 v159, 0x3377d1cf, v157
	v_fmac_f32_e32 v159, 0x3f317217, v157
	s_nop 1
	v_mov_b32_e32 v157, v159
	v_pk_mul_f32 v[198:199], v[156:157], v[154:155] op_sel_hi:[0,1]
	v_pk_mul_f32 v[196:197], v[196:197], v[198:199]
	v_max_f32_e32 v159, 0xc2700000, v157
	v_pk_mul_f32 v[196:197], v[196:197], s[10:11] op_sel_hi:[1,0]
	s_nop 0
	v_exp_f32_e32 v196, v196
	v_exp_f32_e32 v197, v197
	s_nop 0
	v_pk_add_f32 v[196:197], v[196:197], 1.0 op_sel_hi:[1,0]
	s_nop 0
	v_rcp_f32_e32 v196, v196
	v_rcp_f32_e32 v197, v197
	s_nop 0
	v_pk_fma_f32 v[196:197], v[188:189], v[196:197], v[138:139]
	s_nop 0
	s_nop 1
	v_log_f32_e32 v157, v196
	s_nop 0
	v_mul_f32_e32 v161, 0x3f317217, v157
	v_fma_f32 v161, v157, s3, -v161
	v_fmac_f32_e32 v161, 0x3377d1cf, v157
	v_fmac_f32_e32 v161, 0x3f317217, v157
	s_nop 1
	v_mov_b32_e32 v157, v161
	v_max_f32_e32 v161, 0xc2700000, v157
	s_nop 0
	v_log_f32_e32 v157, v197
	s_nop 0
	v_mul_f32_e32 v163, 0x3f317217, v157
	v_fma_f32 v163, v157, s3, -v163
	v_fmac_f32_e32 v163, 0x3377d1cf, v157
	v_fmac_f32_e32 v163, 0x3f317217, v157
	s_nop 1
	v_mov_b32_e32 v157, v163
	v_pk_mul_f32 v[196:197], v[156:157], v[152:153] op_sel_hi:[0,1]
	v_pk_mul_f32 v[194:195], v[194:195], v[196:197]
	v_max_f32_e32 v163, 0xc2700000, v157
	v_pk_mul_f32 v[194:195], v[194:195], s[10:11] op_sel_hi:[1,0]
	s_nop 0
	v_exp_f32_e32 v194, v194
	v_exp_f32_e32 v195, v195
	s_nop 0
	v_pk_add_f32 v[194:195], v[194:195], 1.0 op_sel_hi:[1,0]
	s_nop 0
	v_rcp_f32_e32 v194, v194
	v_rcp_f32_e32 v195, v195
	s_nop 0
	v_pk_fma_f32 v[194:195], v[190:191], v[194:195], v[132:133]
	s_nop 0
	s_nop 1
	v_log_f32_e32 v157, v194
	v_cvt_pk_bf16_f32 v194, v66, v159
	v_mul_f32_e32 v165, 0x3f317217, v157
	v_fma_f32 v165, v157, s3, -v165
	v_fmac_f32_e32 v165, 0x3377d1cf, v157
	v_fmac_f32_e32 v165, 0x3f317217, v157
	s_nop 1
	v_mov_b32_e32 v157, v165
	v_max_f32_e32 v165, 0xc2700000, v157
	s_nop 0
	v_log_f32_e32 v157, v195
	v_cvt_pk_bf16_f32 v195, v161, v163
	v_mul_f32_e32 v167, 0x3f317217, v157
	v_fma_f32 v167, v157, s3, -v167
	v_fmac_f32_e32 v167, 0x3377d1cf, v157
	v_fmac_f32_e32 v167, 0x3f317217, v157
	s_nop 1
	v_mov_b32_e32 v157, v167
	v_max_f32_e32 v167, 0xc2700000, v157
	v_pk_mul_f32 v[156:157], v[156:157], v[148:149] op_sel_hi:[0,1]
	v_pk_mul_f32 v[156:157], v[172:173], v[156:157]
	v_cvt_pk_bf16_f32 v196, v165, v167
	v_pk_mul_f32 v[156:157], v[156:157], s[10:11] op_sel_hi:[1,0]
	v_cvt_f32_i32_e32 v173, v43
	v_exp_f32_e32 v156, v156
	v_exp_f32_e32 v157, v157
	v_cvt_f32_i32_e32 v172, v42
	v_pk_add_f32 v[156:157], v[156:157], 1.0 op_sel_hi:[1,0]
	s_nop 0
	v_rcp_f32_e32 v156, v156
	v_rcp_f32_e32 v157, v157
	s_nop 0
	v_pk_fma_f32 v[156:157], v[192:193], v[156:157], v[134:135]
	s_nop 0
	s_nop 1
	v_log_f32_e32 v156, v156
	s_nop 0
	v_mul_f32_e32 v169, 0x3f317217, v156
	v_fma_f32 v169, v156, s3, -v169
	v_fmac_f32_e32 v169, 0x3377d1cf, v156
	v_fmac_f32_e32 v169, 0x3f317217, v156
	s_nop 1
	v_mov_b32_e32 v156, v169
	v_max_f32_e32 v156, 0xc2700000, v156
	v_log_f32_e32 v157, v157
	s_nop 0
	v_mul_f32_e32 v169, 0x3f317217, v157
	v_fma_f32 v169, v157, s3, -v169
	v_fmac_f32_e32 v169, 0x3377d1cf, v157
	v_fmac_f32_e32 v169, 0x3f317217, v157
	s_nop 1
	v_mov_b32_e32 v157, v169
	v_max_f32_e32 v157, 0xc2700000, v157
	v_cvt_pk_bf16_f32 v197, v156, v157
	global_store_dwordx4 v[174:175], v[194:197], off offset:256
	v_cvt_f32_i32_e32 v175, v49
	v_cvt_f32_i32_e32 v174, v48
	v_cvt_f32_i32_e32 v195, v47
	v_cvt_f32_i32_e32 v194, v46
	v_pk_mul_f32 v[196:197], v[158:159], v[170:171] op_sel_hi:[0,1]
	v_cvt_f32_i32_e32 v157, v45
	v_cvt_f32_i32_e32 v156, v44
	v_pk_mul_f32 v[194:195], v[194:195], v[196:197]
	s_nop 0
	v_pk_mul_f32 v[194:195], v[194:195], s[10:11] op_sel_hi:[1,0]
	s_nop 0
	v_exp_f32_e32 v194, v194
	v_exp_f32_e32 v195, v195
	s_nop 0
	v_pk_add_f32 v[194:195], v[194:195], 1.0 op_sel_hi:[1,0]
	s_nop 0
	v_rcp_f32_e32 v194, v194
	v_rcp_f32_e32 v195, v195
	s_nop 0
	v_pk_fma_f32 v[194:195], v[180:181], v[194:195], v[136:137]
	s_nop 0
	s_nop 1
	v_log_f32_e32 v66, v194
	s_nop 0
	v_mul_f32_e32 v159, 0x3f317217, v66
	v_fma_f32 v159, v66, s3, -v159
	v_fmac_f32_e32 v159, 0x3377d1cf, v66
	v_fmac_f32_e32 v159, 0x3f317217, v66
	s_nop 1
	v_mov_b32_e32 v66, v159
	v_max_f32_e32 v66, 0xc2700000, v66
	v_log_f32_e32 v159, v195
	s_nop 0
	v_mul_f32_e32 v161, 0x3f317217, v159
	v_fma_f32 v161, v159, s3, -v161
	v_fmac_f32_e32 v161, 0x3377d1cf, v159
	v_fmac_f32_e32 v161, 0x3f317217, v159
	s_nop 1
	v_mov_b32_e32 v159, v161
	v_pk_mul_f32 v[194:195], v[158:159], v[154:155] op_sel_hi:[0,1]
	v_pk_mul_f32 v[174:175], v[174:175], v[194:195]
	v_max_f32_e32 v161, 0xc2700000, v159
	v_pk_mul_f32 v[174:175], v[174:175], s[10:11] op_sel_hi:[1,0]
	s_nop 0
	v_exp_f32_e32 v174, v174
	v_exp_f32_e32 v175, v175
	s_nop 0
	v_pk_add_f32 v[174:175], v[174:175], 1.0 op_sel_hi:[1,0]
	s_nop 0
	v_rcp_f32_e32 v174, v174
	v_rcp_f32_e32 v175, v175
	s_nop 0
	v_pk_fma_f32 v[174:175], v[188:189], v[174:175], v[138:139]
	s_nop 0
	s_nop 1
	v_log_f32_e32 v159, v174
	s_nop 0
	v_mul_f32_e32 v163, 0x3f317217, v159
	v_fma_f32 v163, v159, s3, -v163
	v_fmac_f32_e32 v163, 0x3377d1cf, v159
	v_fmac_f32_e32 v163, 0x3f317217, v159
	s_nop 1
	v_mov_b32_e32 v159, v163
	v_max_f32_e32 v163, 0xc2700000, v159
	s_nop 0
	v_log_f32_e32 v159, v175
	s_nop 0
	v_mul_f32_e32 v165, 0x3f317217, v159
	v_fma_f32 v165, v159, s3, -v165
	v_fmac_f32_e32 v165, 0x3377d1cf, v159
	v_fmac_f32_e32 v165, 0x3f317217, v159
	s_nop 1
; __device__ __forceinline__ unsigned cvt_pk_bf16(float lo, float hi) { f32x2_t v = {lo, hi}; bf16x2_t b = __builtin_convertvector(v, bf16x2_t); return __builtin_bit_cast(unsigned, b); }
; __device__ __forceinline__ float fast_rcp(float x) { return __builtin_amdgcn_rcpf(x); }
;     template <int KIND>
;     __device__ __forceinline__ void run(const f32x4 (&acc)[2][2][4][2], const Unit& u, int wr, int wc, int fr, int fq) const {
;     ...
;                 for (int m = 0; m < 4; ++m) { const int row = row0 + ai * HALF + m * 16; const float a = __shfl(ai ? sa_hi : sa_lo, 16 * m + fr);
;                     const f32x4 f0 = __builtin_convertvector(__builtin_bit_cast(i32x4, acc[ai][bj][m][0]), f32x4), f1 = __builtin_convertvector(__builtin_bit_cast(i32x4, acc[ai][bj][m][1]), f32x4);
;                     f32x2_t v[4] = {(f32x2_t){f0[0], f0[1]}, (f32x2_t){f0[2], f0[3]}, (f32x2_t){f1[0], f1[1]}, (f32x2_t){f1[2], f1[3]}};
; #pragma unroll
;                     for (int j = 0; j < 4; ++j) {
;                         v[j] = v[j] * (sc2[j] * (f32x2_t){a, a});
;                         if (KIND == 0 || KIND == 1 || KIND == 3) {
;                             const f32x2_t e = v[j] * (f32x2_t){-LOG2E, -LOG2E};
;                             const f32x2_t dn = (f32x2_t){__builtin_amdgcn_exp2f(e[0]), __builtin_amdgcn_exp2f(e[1])} + (f32x2_t){1.0f, 1.0f};
;                             const f32x2_t sg = (f32x2_t){fast_rcp(dn[0]), fast_rcp(dn[1])};
;                             if (KIND == 0) v[j] = v[j] * sg;
;                             else if (KIND == 3) v[j] = (v[j] * sg) * aux2[j];
;                             else { const f32x2_t f = __builtin_elementwise_fma((f32x2_t){1.0f, 1.0f} - aux2[j], sg, aux2[j]);
;                                 v[j] = (f32x2_t){fmaxf(__logf(f[0]), -60.0f), fmaxf(__logf(f[1]), -60.0f)}; }
;                         }
;                     }
;                     u32x4 w; w.x = cvt_pk_bf16(v[0][0], v[0][1]); w.y = cvt_pk_bf16(v[1][0], v[1][1]); w.z = cvt_pk_bf16(v[2][0], v[2][1]); w.w = cvt_pk_bf16(v[3][0], v[3][1]);
;                     *(u32x4*)(O + (size_t)row * NPROJ + col0 + bj * HALF) = w; }
	v_mov_b32_e32 v159, v165
	v_pk_mul_f32 v[174:175], v[158:159], v[152:153] op_sel_hi:[0,1]
	v_pk_mul_f32 v[172:173], v[172:173], v[174:175]
	v_max_f32_e32 v165, 0xc2700000, v159
	v_pk_mul_f32 v[172:173], v[172:173], s[10:11] op_sel_hi:[1,0]
	v_cvt_f32_i32_e32 v175, v39
	v_exp_f32_e32 v172, v172
	v_exp_f32_e32 v173, v173
	v_cvt_f32_i32_e32 v174, v38
	v_pk_add_f32 v[172:173], v[172:173], 1.0 op_sel_hi:[1,0]
	s_nop 0
	v_rcp_f32_e32 v172, v172
	v_rcp_f32_e32 v173, v173
	s_nop 0
	v_pk_fma_f32 v[172:173], v[190:191], v[172:173], v[132:133]
	s_nop 0
	s_nop 1
	v_log_f32_e32 v159, v172
	s_nop 0
	v_mul_f32_e32 v167, 0x3f317217, v159
	v_fma_f32 v167, v159, s3, -v167
	v_fmac_f32_e32 v167, 0x3377d1cf, v159
	v_fmac_f32_e32 v167, 0x3f317217, v159
	s_nop 1
	v_mov_b32_e32 v159, v167
	v_max_f32_e32 v167, 0xc2700000, v159
	s_nop 0
	v_log_f32_e32 v159, v173
	v_cvt_f32_i32_e32 v173, v41
	v_mul_f32_e32 v169, 0x3f317217, v159
	v_fma_f32 v169, v159, s3, -v169
	v_fmac_f32_e32 v169, 0x3377d1cf, v159
	v_fmac_f32_e32 v169, 0x3f317217, v159
	s_nop 1
	v_mov_b32_e32 v159, v169
	v_max_f32_e32 v169, 0xc2700000, v159
	v_pk_mul_f32 v[158:159], v[158:159], v[148:149] op_sel_hi:[0,1]
	v_pk_mul_f32 v[156:157], v[156:157], v[158:159]
	s_nop 0
	v_pk_mul_f32 v[156:157], v[156:157], s[10:11] op_sel_hi:[1,0]
	s_nop 0
	v_exp_f32_e32 v156, v156
	v_exp_f32_e32 v157, v157
	s_nop 0
	v_pk_add_f32 v[156:157], v[156:157], 1.0 op_sel_hi:[1,0]
	s_nop 0
	v_rcp_f32_e32 v156, v156
	v_rcp_f32_e32 v157, v157
	s_nop 0
	v_pk_fma_f32 v[156:157], v[192:193], v[156:157], v[134:135]
	s_nop 0
	s_nop 1
	v_log_f32_e32 v156, v156
	s_nop 0
	v_mul_f32_e32 v158, 0x3f317217, v156
	v_fma_f32 v158, v156, s3, -v158
	v_fmac_f32_e32 v158, 0x3377d1cf, v156
	v_fmac_f32_e32 v158, 0x3f317217, v156
	s_nop 1
	v_mov_b32_e32 v156, v158
	v_max_f32_e32 v159, 0xc2700000, v156
	v_cvt_pk_bf16_f32 v158, v167, v169
	v_log_f32_e32 v156, v157
	s_nop 0
	v_mul_f32_e32 v157, 0x3f317217, v156
	v_fma_f32 v157, v156, s3, -v157
	v_fmac_f32_e32 v157, 0x3377d1cf, v156
	v_fmac_f32_e32 v157, 0x3f317217, v156
	s_nop 1
	v_mov_b32_e32 v156, v157
	v_max_f32_e32 v172, 0xc2700000, v156
	v_cvt_pk_bf16_f32 v156, v66, v161
	v_cvt_pk_bf16_f32 v157, v163, v165
	v_cvt_pk_bf16_f32 v159, v159, v172
	global_store_dwordx4 v[176:177], v[156:159], off offset:256
	v_pk_mul_f32 v[176:177], v[160:161], v[170:171] op_sel_hi:[0,1]
	v_pk_mul_f32 v[174:175], v[174:175], v[176:177]
	v_cvt_f32_i32_e32 v172, v40
	v_pk_mul_f32 v[174:175], v[174:175], s[10:11] op_sel_hi:[1,0]
	v_cvt_f32_i32_e32 v159, v35
	v_exp_f32_e32 v174, v174
	v_exp_f32_e32 v175, v175
	v_cvt_f32_i32_e32 v158, v34
	v_cvt_f32_i32_e32 v157, v37
	v_cvt_f32_i32_e32 v156, v36
	v_pk_add_f32 v[174:175], v[174:175], 1.0 op_sel_hi:[1,0]
	s_nop 0
	v_rcp_f32_e32 v174, v174
	v_rcp_f32_e32 v175, v175
	s_nop 0
	v_pk_fma_f32 v[174:175], v[180:181], v[174:175], v[136:137]
	s_nop 0
	s_nop 1
	v_log_f32_e32 v66, v174
	s_nop 0
	v_mul_f32_e32 v161, 0x3f317217, v66
	v_fma_f32 v161, v66, s3, -v161
	v_fmac_f32_e32 v161, 0x3377d1cf, v66
	v_fmac_f32_e32 v161, 0x3f317217, v66
	s_nop 1
	v_mov_b32_e32 v66, v161
	v_max_f32_e32 v66, 0xc2700000, v66
	v_log_f32_e32 v161, v175
	s_nop 0
	v_mul_f32_e32 v163, 0x3f317217, v161
	v_fma_f32 v163, v161, s3, -v163
	v_fmac_f32_e32 v163, 0x3377d1cf, v161
	v_fmac_f32_e32 v163, 0x3f317217, v161
	s_nop 1
	v_mov_b32_e32 v161, v163
	v_max_f32_e32 v161, 0xc2700000, v161
	v_pk_mul_f32 v[174:175], v[160:161], v[154:155] op_sel_hi:[0,1]
	v_pk_mul_f32 v[172:173], v[172:173], v[174:175]
	s_nop 0
	v_pk_mul_f32 v[172:173], v[172:173], s[10:11] op_sel_hi:[1,0]
	s_nop 0
	v_exp_f32_e32 v172, v172
	v_exp_f32_e32 v173, v173
	s_nop 0
	v_pk_add_f32 v[172:173], v[172:173], 1.0 op_sel_hi:[1,0]
	s_nop 0
	v_rcp_f32_e32 v172, v172
	v_rcp_f32_e32 v173, v173
	s_nop 0
	v_pk_fma_f32 v[172:173], v[188:189], v[172:173], v[138:139]
	s_nop 0
	s_nop 1
	v_log_f32_e32 v163, v172
	s_nop 0
	v_mul_f32_e32 v165, 0x3f317217, v163
	v_fma_f32 v165, v163, s3, -v165
	v_fmac_f32_e32 v165, 0x3377d1cf, v163
	v_fmac_f32_e32 v165, 0x3f317217, v163
	s_nop 1
	v_mov_b32_e32 v163, v165
	v_max_f32_e32 v163, 0xc2700000, v163
	v_log_f32_e32 v165, v173
	v_pk_mul_f32 v[172:173], v[160:161], v[152:153] op_sel_hi:[0,1]
	v_pk_mul_f32 v[158:159], v[158:159], v[172:173]
	v_pk_mul_f32 v[158:159], v[158:159], s[10:11] op_sel_hi:[1,0]
	v_cvt_f32_i32_e32 v173, v31
	v_exp_f32_e32 v158, v158
	v_exp_f32_e32 v159, v159
	v_mul_f32_e32 v167, 0x3f317217, v165
	v_fma_f32 v167, v165, s3, -v167
	v_fmac_f32_e32 v167, 0x3377d1cf, v165
	v_pk_add_f32 v[158:159], v[158:159], 1.0 op_sel_hi:[1,0]
	v_fmac_f32_e32 v167, 0x3f317217, v165
	v_rcp_f32_e32 v158, v158
	v_rcp_f32_e32 v159, v159
	v_cvt_f32_i32_e32 v172, v30
	v_pk_mul_f32 v[174:175], v[162:163], v[170:171] op_sel_hi:[0,1]
	v_pk_fma_f32 v[158:159], v[190:191], v[158:159], v[132:133]
	v_mov_b32_e32 v165, v167
	v_pk_mul_f32 v[172:173], v[172:173], v[174:175]
	v_log_f32_e32 v158, v158
	v_pk_mul_f32 v[172:173], v[172:173], s[10:11] op_sel_hi:[1,0]
	v_max_f32_e32 v165, 0xc2700000, v165
	v_exp_f32_e32 v172, v172
	v_mul_f32_e32 v167, 0x3f317217, v158
	v_fma_f32 v167, v158, s3, -v167
	v_fmac_f32_e32 v167, 0x3377d1cf, v158
	v_fmac_f32_e32 v167, 0x3f317217, v158
	v_exp_f32_e32 v173, v173
	s_nop 0
	v_mov_b32_e32 v158, v167
	v_max_f32_e32 v167, 0xc2700000, v158
	v_pk_add_f32 v[172:173], v[172:173], 1.0 op_sel_hi:[1,0]
	v_log_f32_e32 v158, v159
	v_rcp_f32_e32 v172, v172
	v_rcp_f32_e32 v173, v173
	v_mul_f32_e32 v159, 0x3f317217, v158
	v_fma_f32 v159, v158, s3, -v159
	v_fmac_f32_e32 v159, 0x3377d1cf, v158
	v_fmac_f32_e32 v159, 0x3f317217, v158
	v_pk_fma_f32 v[172:173], v[180:181], v[172:173], v[136:137]
	s_nop 0
	v_mov_b32_e32 v158, v159
; __device__ __forceinline__ unsigned cvt_pk_bf16(float lo, float hi) { f32x2_t v = {lo, hi}; bf16x2_t b = __builtin_convertvector(v, bf16x2_t); return __builtin_bit_cast(unsigned, b); }
; __device__ __forceinline__ float fast_rcp(float x) { return __builtin_amdgcn_rcpf(x); }
;     template <int KIND>
;     __device__ __forceinline__ void run(const f32x4 (&acc)[2][2][4][2], const Unit& u, int wr, int wc, int fr, int fq) const {
;     ...
;                 for (int m = 0; m < 4; ++m) { const int row = row0 + ai * HALF + m * 16; const float a = __shfl(ai ? sa_hi : sa_lo, 16 * m + fr);
;                     const f32x4 f0 = __builtin_convertvector(__builtin_bit_cast(i32x4, acc[ai][bj][m][0]), f32x4), f1 = __builtin_convertvector(__builtin_bit_cast(i32x4, acc[ai][bj][m][1]), f32x4);
;                     f32x2_t v[4] = {(f32x2_t){f0[0], f0[1]}, (f32x2_t){f0[2], f0[3]}, (f32x2_t){f1[0], f1[1]}, (f32x2_t){f1[2], f1[3]}};
; #pragma unroll
;                     for (int j = 0; j < 4; ++j) {
;                         v[j] = v[j] * (sc2[j] * (f32x2_t){a, a});
;                         if (KIND == 0 || KIND == 1 || KIND == 3) {
;                             const f32x2_t e = v[j] * (f32x2_t){-LOG2E, -LOG2E};
;                             const f32x2_t dn = (f32x2_t){__builtin_amdgcn_exp2f(e[0]), __builtin_amdgcn_exp2f(e[1])} + (f32x2_t){1.0f, 1.0f};
;                             const f32x2_t sg = (f32x2_t){fast_rcp(dn[0]), fast_rcp(dn[1])};
;                             if (KIND == 0) v[j] = v[j] * sg;
;                             else if (KIND == 3) v[j] = (v[j] * sg) * aux2[j];
;                             else { const f32x2_t f = __builtin_elementwise_fma((f32x2_t){1.0f, 1.0f} - aux2[j], sg, aux2[j]);
;                                 v[j] = (f32x2_t){fmaxf(__logf(f[0]), -60.0f), fmaxf(__logf(f[1]), -60.0f)}; }
;                         }
;                     }
;                     u32x4 w; w.x = cvt_pk_bf16(v[0][0], v[0][1]); w.y = cvt_pk_bf16(v[1][0], v[1][1]); w.z = cvt_pk_bf16(v[2][0], v[2][1]); w.w = cvt_pk_bf16(v[3][0], v[3][1]);
;                     *(u32x4*)(O + (size_t)row * NPROJ + col0 + bj * HALF) = w; }
	v_max_f32_e32 v169, 0xc2700000, v158
	v_pk_mul_f32 v[158:159], v[160:161], v[148:149] op_sel_hi:[0,1]
	v_pk_mul_f32 v[156:157], v[156:157], v[158:159]
	s_nop 0
	v_pk_mul_f32 v[156:157], v[156:157], s[10:11] op_sel_hi:[1,0]
	s_nop 0
	v_exp_f32_e32 v156, v156
	v_exp_f32_e32 v157, v157
	s_nop 0
	v_pk_add_f32 v[156:157], v[156:157], 1.0 op_sel_hi:[1,0]
	s_nop 0
	v_rcp_f32_e32 v156, v156
	v_rcp_f32_e32 v157, v157
	s_nop 0
	v_pk_fma_f32 v[156:157], v[192:193], v[156:157], v[134:135]
	s_nop 0
	s_nop 1
	v_log_f32_e32 v156, v156
	s_nop 0
	v_mul_f32_e32 v158, 0x3f317217, v156
	v_fma_f32 v158, v156, s3, -v158
	v_fmac_f32_e32 v158, 0x3377d1cf, v156
	v_fmac_f32_e32 v158, 0x3f317217, v156
	s_nop 1
	v_mov_b32_e32 v156, v158
	v_max_f32_e32 v159, 0xc2700000, v156
	v_cvt_pk_bf16_f32 v158, v167, v169
	v_log_f32_e32 v156, v157
	s_nop 0
	v_mul_f32_e32 v157, 0x3f317217, v156
	v_fma_f32 v157, v156, s3, -v157
	v_fmac_f32_e32 v157, 0x3377d1cf, v156
	v_fmac_f32_e32 v157, 0x3f317217, v156
	s_nop 1
	v_mov_b32_e32 v156, v157
	v_max_f32_e32 v160, 0xc2700000, v156
	v_cvt_pk_bf16_f32 v156, v66, v161
	v_log_f32_e32 v66, v172
	v_cvt_pk_bf16_f32 v157, v163, v165
	v_cvt_pk_bf16_f32 v159, v159, v160
	v_cvt_f32_i32_e32 v161, v33
	v_mul_f32_e32 v163, 0x3f317217, v66
	v_fma_f32 v163, v66, s3, -v163
	v_fmac_f32_e32 v163, 0x3377d1cf, v66
	v_fmac_f32_e32 v163, 0x3f317217, v66
	v_cvt_f32_i32_e32 v160, v32
	global_store_dwordx4 v[178:179], v[156:159], off offset:256
	v_mov_b32_e32 v66, v163
	s_nop 0
	v_cvt_f32_i32_e32 v159, v27
	v_log_f32_e32 v163, v173
	v_cvt_f32_i32_e32 v158, v26
	v_cvt_f32_i32_e32 v157, v29
	v_cvt_f32_i32_e32 v156, v28
	v_mul_f32_e32 v165, 0x3f317217, v163
	v_fma_f32 v165, v163, s3, -v165
	v_fmac_f32_e32 v165, 0x3377d1cf, v163
	v_fmac_f32_e32 v165, 0x3f317217, v163
	v_max_f32_e32 v66, 0xc2700000, v66
	s_nop 0
	v_mov_b32_e32 v163, v165
	v_max_f32_e32 v163, 0xc2700000, v163
	v_pk_mul_f32 v[172:173], v[162:163], v[154:155] op_sel_hi:[0,1]
	v_pk_mul_f32 v[160:161], v[160:161], v[172:173]
	s_nop 0
	v_pk_mul_f32 v[160:161], v[160:161], s[10:11] op_sel_hi:[1,0]
	s_nop 0
	v_exp_f32_e32 v160, v160
	v_exp_f32_e32 v161, v161
	s_nop 0
	v_pk_add_f32 v[160:161], v[160:161], 1.0 op_sel_hi:[1,0]
	s_nop 0
	v_rcp_f32_e32 v160, v160
	v_rcp_f32_e32 v161, v161
	s_nop 0
	v_pk_fma_f32 v[160:161], v[188:189], v[160:161], v[138:139]
	s_nop 0
	s_nop 1
	v_log_f32_e32 v160, v160
	s_nop 0
	v_mul_f32_e32 v165, 0x3f317217, v160
	v_fma_f32 v165, v160, s3, -v165
	v_fmac_f32_e32 v165, 0x3377d1cf, v160
	v_fmac_f32_e32 v165, 0x3f317217, v160
	s_nop 1
	v_mov_b32_e32 v160, v165
	v_max_f32_e32 v165, 0xc2700000, v160
	v_pk_mul_f32 v[172:173], v[164:165], v[170:171] op_sel_hi:[0,1]
	v_log_f32_e32 v160, v161
	s_nop 0
	v_mul_f32_e32 v161, 0x3f317217, v160
	v_fma_f32 v161, v160, s3, -v161
	v_fmac_f32_e32 v161, 0x3377d1cf, v160
	v_fmac_f32_e32 v161, 0x3f317217, v160
	s_nop 1
	v_mov_b32_e32 v160, v161
	v_max_f32_e32 v167, 0xc2700000, v160
	v_pk_mul_f32 v[160:161], v[162:163], v[152:153] op_sel_hi:[0,1]
	v_pk_mul_f32 v[158:159], v[158:159], v[160:161]
	s_nop 0
	v_pk_mul_f32 v[158:159], v[158:159], s[10:11] op_sel_hi:[1,0]
	s_nop 0
	v_exp_f32_e32 v158, v158
	v_exp_f32_e32 v159, v159
	s_nop 0
	v_pk_add_f32 v[158:159], v[158:159], 1.0 op_sel_hi:[1,0]
	s_nop 0
	v_rcp_f32_e32 v158, v158
	v_rcp_f32_e32 v159, v159
	s_nop 0
	v_pk_fma_f32 v[158:159], v[190:191], v[158:159], v[132:133]
	s_nop 0
	s_nop 1
	v_log_f32_e32 v158, v158
	s_nop 0
	v_mul_f32_e32 v160, 0x3f317217, v158
	v_fma_f32 v160, v158, s3, -v160
	v_fmac_f32_e32 v160, 0x3377d1cf, v158
	v_fmac_f32_e32 v160, 0x3f317217, v158
	s_nop 1
	v_mov_b32_e32 v158, v160
	v_max_f32_e32 v160, 0xc2700000, v158
	s_nop 0
	v_log_f32_e32 v158, v159
	s_nop 0
	v_mul_f32_e32 v159, 0x3f317217, v158
	v_fma_f32 v159, v158, s3, -v159
	v_fmac_f32_e32 v159, 0x3377d1cf, v158
	v_fmac_f32_e32 v159, 0x3f317217, v158
	s_nop 1
	v_mov_b32_e32 v158, v159
	v_max_f32_e32 v161, 0xc2700000, v158
	v_pk_mul_f32 v[158:159], v[162:163], v[148:149] op_sel_hi:[0,1]
	v_pk_mul_f32 v[156:157], v[156:157], v[158:159]
	s_nop 0
	v_pk_mul_f32 v[156:157], v[156:157], s[10:11] op_sel_hi:[1,0]
	s_nop 0
	v_exp_f32_e32 v156, v156
	v_exp_f32_e32 v157, v157
	s_nop 0
	v_pk_add_f32 v[156:157], v[156:157], 1.0 op_sel_hi:[1,0]
	s_nop 0
	v_rcp_f32_e32 v156, v156
	v_rcp_f32_e32 v157, v157
	s_nop 0
	v_pk_fma_f32 v[156:157], v[192:193], v[156:157], v[134:135]
	s_nop 0
	s_nop 1
	v_log_f32_e32 v156, v156
	s_nop 0
	v_mul_f32_e32 v158, 0x3f317217, v156
	v_fma_f32 v158, v156, s3, -v158
	v_fmac_f32_e32 v158, 0x3377d1cf, v156
	v_fmac_f32_e32 v158, 0x3f317217, v156
	s_nop 1
	v_mov_b32_e32 v156, v158
	v_max_f32_e32 v159, 0xc2700000, v156
	v_cvt_pk_bf16_f32 v158, v160, v161
	v_log_f32_e32 v156, v157
	v_cvt_f32_i32_e32 v161, v25
	v_cvt_f32_i32_e32 v160, v24
	v_mul_f32_e32 v157, 0x3f317217, v156
	v_fma_f32 v157, v156, s3, -v157
	v_fmac_f32_e32 v157, 0x3377d1cf, v156
	v_fmac_f32_e32 v157, 0x3f317217, v156
	s_nop 1
	v_mov_b32_e32 v156, v157
	v_max_f32_e32 v162, 0xc2700000, v156
	v_cvt_pk_bf16_f32 v156, v66, v163
	v_cvt_pk_bf16_f32 v159, v159, v162
	v_cvt_f32_i32_e32 v163, v23
	v_cvt_f32_i32_e32 v162, v22
	v_cvt_pk_bf16_f32 v157, v165, v167
	global_store_dwordx4 v[182:183], v[156:159], off offset:256
	v_pk_mul_f32 v[162:163], v[162:163], v[172:173]
	s_nop 0
	v_pk_mul_f32 v[162:163], v[162:163], s[10:11] op_sel_hi:[1,0]
	v_cvt_f32_i32_e32 v159, v19
	v_exp_f32_e32 v162, v162
	v_exp_f32_e32 v163, v163
	v_cvt_f32_i32_e32 v158, v18
	v_cvt_f32_i32_e32 v157, v21
	v_cvt_f32_i32_e32 v156, v20
	v_pk_add_f32 v[162:163], v[162:163], 1.0 op_sel_hi:[1,0]
	s_nop 0
	v_rcp_f32_e32 v162, v162
	v_rcp_f32_e32 v163, v163
	s_nop 0
; __device__ __forceinline__ unsigned cvt_pk_bf16(float lo, float hi) { f32x2_t v = {lo, hi}; bf16x2_t b = __builtin_convertvector(v, bf16x2_t); return __builtin_bit_cast(unsigned, b); }
; __device__ __forceinline__ float fast_rcp(float x) { return __builtin_amdgcn_rcpf(x); }
;     template <int KIND>
;     __device__ __forceinline__ void run(const f32x4 (&acc)[2][2][4][2], const Unit& u, int wr, int wc, int fr, int fq) const {
;     ...
;                 for (int m = 0; m < 4; ++m) { const int row = row0 + ai * HALF + m * 16; const float a = __shfl(ai ? sa_hi : sa_lo, 16 * m + fr);
;                     const f32x4 f0 = __builtin_convertvector(__builtin_bit_cast(i32x4, acc[ai][bj][m][0]), f32x4), f1 = __builtin_convertvector(__builtin_bit_cast(i32x4, acc[ai][bj][m][1]), f32x4);
;                     f32x2_t v[4] = {(f32x2_t){f0[0], f0[1]}, (f32x2_t){f0[2], f0[3]}, (f32x2_t){f1[0], f1[1]}, (f32x2_t){f1[2], f1[3]}};
; #pragma unroll
;                     for (int j = 0; j < 4; ++j) {
;                         v[j] = v[j] * (sc2[j] * (f32x2_t){a, a});
;                         if (KIND == 0 || KIND == 1 || KIND == 3) {
;                             const f32x2_t e = v[j] * (f32x2_t){-LOG2E, -LOG2E};
;                             const f32x2_t dn = (f32x2_t){__builtin_amdgcn_exp2f(e[0]), __builtin_amdgcn_exp2f(e[1])} + (f32x2_t){1.0f, 1.0f};
;                             const f32x2_t sg = (f32x2_t){fast_rcp(dn[0]), fast_rcp(dn[1])};
;                             if (KIND == 0) v[j] = v[j] * sg;
;                             else if (KIND == 3) v[j] = (v[j] * sg) * aux2[j];
;                             else { const f32x2_t f = __builtin_elementwise_fma((f32x2_t){1.0f, 1.0f} - aux2[j], sg, aux2[j]);
;                                 v[j] = (f32x2_t){fmaxf(__logf(f[0]), -60.0f), fmaxf(__logf(f[1]), -60.0f)}; }
;                         }
;                     }
;                     u32x4 w; w.x = cvt_pk_bf16(v[0][0], v[0][1]); w.y = cvt_pk_bf16(v[1][0], v[1][1]); w.z = cvt_pk_bf16(v[2][0], v[2][1]); w.w = cvt_pk_bf16(v[3][0], v[3][1]);
;                     *(u32x4*)(O + (size_t)row * NPROJ + col0 + bj * HALF) = w; }
	v_pk_fma_f32 v[162:163], v[180:181], v[162:163], v[136:137]
	s_nop 0
	s_nop 1
	v_log_f32_e32 v66, v162
	s_nop 0
	v_mul_f32_e32 v162, 0x3f317217, v66
	v_fma_f32 v162, v66, s3, -v162
	v_fmac_f32_e32 v162, 0x3377d1cf, v66
	v_fmac_f32_e32 v162, 0x3f317217, v66
	s_nop 1
	v_mov_b32_e32 v66, v162
	v_max_f32_e32 v66, 0xc2700000, v66
	v_log_f32_e32 v162, v163
	s_nop 0
	v_mul_f32_e32 v163, 0x3f317217, v162
	v_fma_f32 v163, v162, s3, -v163
	v_fmac_f32_e32 v163, 0x3377d1cf, v162
	v_fmac_f32_e32 v163, 0x3f317217, v162
	s_nop 1
	v_mov_b32_e32 v162, v163
	v_max_f32_e32 v165, 0xc2700000, v162
	v_pk_mul_f32 v[162:163], v[164:165], v[154:155] op_sel_hi:[0,1]
	v_pk_mul_f32 v[160:161], v[160:161], v[162:163]
	s_nop 0
	v_pk_mul_f32 v[160:161], v[160:161], s[10:11] op_sel_hi:[1,0]
	s_nop 0
	v_exp_f32_e32 v160, v160
	v_exp_f32_e32 v161, v161
	s_nop 0
	v_pk_add_f32 v[160:161], v[160:161], 1.0 op_sel_hi:[1,0]
	s_nop 0
	v_rcp_f32_e32 v160, v160
	v_rcp_f32_e32 v161, v161
	s_nop 0
	v_pk_fma_f32 v[160:161], v[188:189], v[160:161], v[138:139]
	s_nop 0
	s_nop 1
	v_log_f32_e32 v160, v160
	s_nop 0
	v_mul_f32_e32 v162, 0x3f317217, v160
	v_fma_f32 v162, v160, s3, -v162
	v_fmac_f32_e32 v162, 0x3377d1cf, v160
	v_fmac_f32_e32 v162, 0x3f317217, v160
	s_nop 1
	v_mov_b32_e32 v160, v162
	v_max_f32_e32 v162, 0xc2700000, v160
	s_nop 0
	v_log_f32_e32 v160, v161
	s_nop 0
	v_mul_f32_e32 v161, 0x3f317217, v160
	v_fma_f32 v161, v160, s3, -v161
	v_fmac_f32_e32 v161, 0x3377d1cf, v160
	v_fmac_f32_e32 v161, 0x3f317217, v160
	s_nop 1
	v_mov_b32_e32 v160, v161
	v_max_f32_e32 v163, 0xc2700000, v160
	v_pk_mul_f32 v[160:161], v[164:165], v[152:153] op_sel_hi:[0,1]
	v_pk_mul_f32 v[158:159], v[158:159], v[160:161]
	s_nop 0
	v_pk_mul_f32 v[158:159], v[158:159], s[10:11] op_sel_hi:[1,0]
	s_nop 0
	v_exp_f32_e32 v158, v158
	v_exp_f32_e32 v159, v159
	s_nop 0
	v_pk_add_f32 v[158:159], v[158:159], 1.0 op_sel_hi:[1,0]
	s_nop 0
	v_rcp_f32_e32 v158, v158
	v_rcp_f32_e32 v159, v159
	s_nop 0
	v_pk_fma_f32 v[158:159], v[190:191], v[158:159], v[132:133]
	s_nop 0
	s_nop 1
	v_log_f32_e32 v158, v158
	s_nop 0
	v_mul_f32_e32 v160, 0x3f317217, v158
	v_fma_f32 v160, v158, s3, -v160
	v_fmac_f32_e32 v160, 0x3377d1cf, v158
	v_fmac_f32_e32 v160, 0x3f317217, v158
	s_nop 1
	v_mov_b32_e32 v158, v160
	v_max_f32_e32 v160, 0xc2700000, v158
	s_nop 0
	v_log_f32_e32 v158, v159
	s_nop 0
	v_mul_f32_e32 v159, 0x3f317217, v158
	v_fma_f32 v159, v158, s3, -v159
	v_fmac_f32_e32 v159, 0x3377d1cf, v158
	v_fmac_f32_e32 v159, 0x3f317217, v158
	s_nop 1
	v_mov_b32_e32 v158, v159
	v_max_f32_e32 v161, 0xc2700000, v158
	v_pk_mul_f32 v[158:159], v[164:165], v[148:149] op_sel_hi:[0,1]
	v_pk_mul_f32 v[156:157], v[156:157], v[158:159]
	s_nop 0
	v_pk_mul_f32 v[156:157], v[156:157], s[10:11] op_sel_hi:[1,0]
	s_nop 0
	v_exp_f32_e32 v156, v156
	v_exp_f32_e32 v157, v157
	s_nop 0
	v_pk_add_f32 v[156:157], v[156:157], 1.0 op_sel_hi:[1,0]
	s_nop 0
	v_rcp_f32_e32 v156, v156
	v_rcp_f32_e32 v157, v157
	s_nop 0
	v_pk_fma_f32 v[156:157], v[192:193], v[156:157], v[134:135]
	s_nop 0
	s_nop 1
	v_log_f32_e32 v156, v156
	s_nop 0
	v_mul_f32_e32 v158, 0x3f317217, v156
	v_fma_f32 v158, v156, s3, -v158
	v_fmac_f32_e32 v158, 0x3377d1cf, v156
	v_fmac_f32_e32 v158, 0x3f317217, v156
	s_nop 1
	v_mov_b32_e32 v156, v158
	v_max_f32_e32 v159, 0xc2700000, v156
	v_cvt_pk_bf16_f32 v158, v160, v161
	v_log_f32_e32 v156, v157
	v_cvt_f32_i32_e32 v161, v17
	v_cvt_f32_i32_e32 v160, v16
	v_mul_f32_e32 v157, 0x3f317217, v156
	v_fma_f32 v157, v156, s3, -v157
	v_fmac_f32_e32 v157, 0x3377d1cf, v156
	v_fmac_f32_e32 v157, 0x3f317217, v156
	s_nop 1
	v_mov_b32_e32 v156, v157
	v_cvt_pk_bf16_f32 v157, v162, v163
	v_cvt_f32_i32_e32 v163, v15
	v_cvt_f32_i32_e32 v162, v14
	v_max_f32_e32 v164, 0xc2700000, v156
	v_cvt_pk_bf16_f32 v156, v66, v165
	v_cvt_pk_bf16_f32 v159, v159, v164
	v_pk_mul_f32 v[164:165], v[166:167], v[170:171] op_sel_hi:[0,1]
	v_pk_mul_f32 v[162:163], v[162:163], v[164:165]
	global_store_dwordx4 v[184:185], v[156:159], off offset:256
	v_pk_mul_f32 v[162:163], v[162:163], s[10:11] op_sel_hi:[1,0]
	s_nop 0
	v_exp_f32_e32 v162, v162
	v_exp_f32_e32 v163, v163
	v_cvt_f32_i32_e32 v159, v11
	v_cvt_f32_i32_e32 v158, v10
	v_cvt_f32_i32_e32 v157, v13
	v_pk_add_f32 v[162:163], v[162:163], 1.0 op_sel_hi:[1,0]
	v_cvt_f32_i32_e32 v156, v12
	v_rcp_f32_e32 v162, v162
	v_rcp_f32_e32 v163, v163
	s_nop 0
	v_pk_fma_f32 v[162:163], v[180:181], v[162:163], v[136:137]
	s_nop 0
	s_nop 1
	v_log_f32_e32 v66, v162
	s_nop 0
	v_mul_f32_e32 v162, 0x3f317217, v66
	v_fma_f32 v162, v66, s3, -v162
	v_fmac_f32_e32 v162, 0x3377d1cf, v66
	v_fmac_f32_e32 v162, 0x3f317217, v66
	s_nop 1
	v_mov_b32_e32 v66, v162
	v_max_f32_e32 v66, 0xc2700000, v66
	v_log_f32_e32 v162, v163
	s_nop 0
	v_mul_f32_e32 v163, 0x3f317217, v162
	v_fma_f32 v163, v162, s3, -v163
	v_fmac_f32_e32 v163, 0x3377d1cf, v162
	v_fmac_f32_e32 v163, 0x3f317217, v162
	s_nop 1
	v_mov_b32_e32 v162, v163
	v_max_f32_e32 v164, 0xc2700000, v162
	v_pk_mul_f32 v[162:163], v[166:167], v[154:155] op_sel_hi:[0,1]
	v_pk_mul_f32 v[160:161], v[160:161], v[162:163]
	v_pk_mul_f32 v[154:155], v[168:169], v[154:155] op_sel_hi:[0,1]
	v_pk_mul_f32 v[160:161], v[160:161], s[10:11] op_sel_hi:[1,0]
	s_nop 0
	v_exp_f32_e32 v160, v160
	v_exp_f32_e32 v161, v161
	s_nop 0
	v_pk_add_f32 v[160:161], v[160:161], 1.0 op_sel_hi:[1,0]
	s_nop 0
	v_rcp_f32_e32 v160, v160
	v_rcp_f32_e32 v161, v161
	s_nop 0
	v_pk_fma_f32 v[160:161], v[188:189], v[160:161], v[138:139]
	s_nop 0
	s_nop 1
	v_log_f32_e32 v160, v160
	s_nop 0
	v_mul_f32_e32 v162, 0x3f317217, v160
	v_fma_f32 v162, v160, s3, -v162
	v_fmac_f32_e32 v162, 0x3377d1cf, v160
	v_fmac_f32_e32 v162, 0x3f317217, v160
	s_nop 1
	v_mov_b32_e32 v160, v162
; __device__ __forceinline__ unsigned cvt_pk_bf16(float lo, float hi) { f32x2_t v = {lo, hi}; bf16x2_t b = __builtin_convertvector(v, bf16x2_t); return __builtin_bit_cast(unsigned, b); }
; __device__ __forceinline__ float fast_rcp(float x) { return __builtin_amdgcn_rcpf(x); }
;     template <int KIND>
;     __device__ __forceinline__ void run(const f32x4 (&acc)[2][2][4][2], const Unit& u, int wr, int wc, int fr, int fq) const {
;     ...
;                 for (int m = 0; m < 4; ++m) { const int row = row0 + ai * HALF + m * 16; const float a = __shfl(ai ? sa_hi : sa_lo, 16 * m + fr);
;                     const f32x4 f0 = __builtin_convertvector(__builtin_bit_cast(i32x4, acc[ai][bj][m][0]), f32x4), f1 = __builtin_convertvector(__builtin_bit_cast(i32x4, acc[ai][bj][m][1]), f32x4);
;                     f32x2_t v[4] = {(f32x2_t){f0[0], f0[1]}, (f32x2_t){f0[2], f0[3]}, (f32x2_t){f1[0], f1[1]}, (f32x2_t){f1[2], f1[3]}};
; #pragma unroll
;                     for (int j = 0; j < 4; ++j) {
;                         v[j] = v[j] * (sc2[j] * (f32x2_t){a, a});
;                         if (KIND == 0 || KIND == 1 || KIND == 3) {
;                             const f32x2_t e = v[j] * (f32x2_t){-LOG2E, -LOG2E};
;                             const f32x2_t dn = (f32x2_t){__builtin_amdgcn_exp2f(e[0]), __builtin_amdgcn_exp2f(e[1])} + (f32x2_t){1.0f, 1.0f};
;                             const f32x2_t sg = (f32x2_t){fast_rcp(dn[0]), fast_rcp(dn[1])};
;                             if (KIND == 0) v[j] = v[j] * sg;
;                             else if (KIND == 3) v[j] = (v[j] * sg) * aux2[j];
;                             else { const f32x2_t f = __builtin_elementwise_fma((f32x2_t){1.0f, 1.0f} - aux2[j], sg, aux2[j]);
;                                 v[j] = (f32x2_t){fmaxf(__logf(f[0]), -60.0f), fmaxf(__logf(f[1]), -60.0f)}; }
;                         }
;                     }
;                     u32x4 w; w.x = cvt_pk_bf16(v[0][0], v[0][1]); w.y = cvt_pk_bf16(v[1][0], v[1][1]); w.z = cvt_pk_bf16(v[2][0], v[2][1]); w.w = cvt_pk_bf16(v[3][0], v[3][1]);
;                     *(u32x4*)(O + (size_t)row * NPROJ + col0 + bj * HALF) = w; }
	v_max_f32_e32 v162, 0xc2700000, v160
	s_nop 0
	v_log_f32_e32 v160, v161
	s_nop 0
	v_mul_f32_e32 v161, 0x3f317217, v160
	v_fma_f32 v161, v160, s3, -v161
	v_fmac_f32_e32 v161, 0x3377d1cf, v160
	v_fmac_f32_e32 v161, 0x3f317217, v160
	s_nop 1
	v_mov_b32_e32 v160, v161
	v_max_f32_e32 v163, 0xc2700000, v160
	v_pk_mul_f32 v[160:161], v[166:167], v[152:153] op_sel_hi:[0,1]
	v_pk_mul_f32 v[158:159], v[158:159], v[160:161]
	v_pk_mul_f32 v[152:153], v[168:169], v[152:153] op_sel_hi:[0,1]
	v_pk_mul_f32 v[158:159], v[158:159], s[10:11] op_sel_hi:[1,0]
	s_nop 0
	v_exp_f32_e32 v158, v158
	v_exp_f32_e32 v159, v159
	s_nop 0
	v_pk_add_f32 v[158:159], v[158:159], 1.0 op_sel_hi:[1,0]
	s_nop 0
	v_rcp_f32_e32 v158, v158
	v_rcp_f32_e32 v159, v159
	s_nop 0
	v_pk_fma_f32 v[158:159], v[190:191], v[158:159], v[132:133]
	s_nop 0
	s_nop 1
	v_log_f32_e32 v158, v158
	s_nop 0
	v_mul_f32_e32 v160, 0x3f317217, v158
	v_fma_f32 v160, v158, s3, -v160
	v_fmac_f32_e32 v160, 0x3377d1cf, v158
	v_fmac_f32_e32 v160, 0x3f317217, v158
	s_nop 1
	v_mov_b32_e32 v158, v160
	v_max_f32_e32 v160, 0xc2700000, v158
	s_nop 0
	v_log_f32_e32 v158, v159
	s_nop 0
	v_mul_f32_e32 v159, 0x3f317217, v158
	v_fma_f32 v159, v158, s3, -v159
	v_fmac_f32_e32 v159, 0x3377d1cf, v158
	v_fmac_f32_e32 v159, 0x3f317217, v158
	s_nop 1
	v_mov_b32_e32 v158, v159
	v_max_f32_e32 v161, 0xc2700000, v158
	v_pk_mul_f32 v[158:159], v[166:167], v[148:149] op_sel_hi:[0,1]
	v_pk_mul_f32 v[156:157], v[156:157], v[158:159]
	v_pk_mul_f32 v[148:149], v[168:169], v[148:149] op_sel_hi:[0,1]
	v_pk_mul_f32 v[156:157], v[156:157], s[10:11] op_sel_hi:[1,0]
	s_nop 0
	v_exp_f32_e32 v156, v156
	v_exp_f32_e32 v157, v157
	s_nop 0
	v_pk_add_f32 v[156:157], v[156:157], 1.0 op_sel_hi:[1,0]
	s_nop 0
	v_rcp_f32_e32 v156, v156
	v_rcp_f32_e32 v157, v157
	s_nop 0
	v_pk_fma_f32 v[156:157], v[192:193], v[156:157], v[134:135]
	s_nop 0
	s_nop 1
	v_log_f32_e32 v156, v156
	s_nop 0
	v_mul_f32_e32 v158, 0x3f317217, v156
	v_fma_f32 v158, v156, s3, -v158
	v_fmac_f32_e32 v158, 0x3377d1cf, v156
	v_fmac_f32_e32 v158, 0x3f317217, v156
	s_nop 1
	v_mov_b32_e32 v156, v158
	v_max_f32_e32 v159, 0xc2700000, v156
	v_cvt_pk_bf16_f32 v158, v160, v161
	v_log_f32_e32 v156, v157
	v_cvt_f32_i32_e32 v161, v9
	v_cvt_f32_i32_e32 v160, v8
	v_mul_f32_e32 v157, 0x3f317217, v156
	v_fma_f32 v157, v156, s3, -v157
	v_fmac_f32_e32 v157, 0x3377d1cf, v156
	v_fmac_f32_e32 v157, 0x3f317217, v156
	v_pk_mul_f32 v[154:155], v[160:161], v[154:155]
	s_nop 0
	v_mov_b32_e32 v156, v157
	v_cvt_pk_bf16_f32 v157, v162, v163
	v_cvt_f32_i32_e32 v163, v7
	v_cvt_f32_i32_e32 v162, v6
	v_max_f32_e32 v165, 0xc2700000, v156
	v_cvt_pk_bf16_f32 v156, v66, v164
	v_cvt_pk_bf16_f32 v159, v159, v165
	v_pk_mul_f32 v[164:165], v[168:169], v[170:171] op_sel_hi:[0,1]
	v_pk_mul_f32 v[162:163], v[162:163], v[164:165]
	v_pk_mul_f32 v[154:155], v[154:155], s[10:11] op_sel_hi:[1,0]
	v_pk_mul_f32 v[162:163], v[162:163], s[10:11] op_sel_hi:[1,0]
	v_exp_f32_e32 v154, v154
	v_exp_f32_e32 v162, v162
	v_exp_f32_e32 v163, v163
	v_exp_f32_e32 v155, v155
	global_store_dwordx4 v[186:187], v[156:159], off offset:256
	v_pk_add_f32 v[162:163], v[162:163], 1.0 op_sel_hi:[1,0]
	s_nop 0
	v_rcp_f32_e32 v162, v162
	v_rcp_f32_e32 v163, v163
	v_pk_add_f32 v[154:155], v[154:155], 1.0 op_sel_hi:[1,0]
	v_cvt_f32_i32_e32 v159, v3
	v_rcp_f32_e32 v154, v154
	v_pk_fma_f32 v[136:137], v[180:181], v[162:163], v[136:137]
	v_rcp_f32_e32 v155, v155
	v_cvt_f32_i32_e32 v158, v2
	v_cvt_f32_i32_e32 v157, v5
	v_log_f32_e32 v66, v136
	v_pk_fma_f32 v[138:139], v[188:189], v[154:155], v[138:139]
	v_pk_mul_f32 v[152:153], v[158:159], v[152:153]
	v_cvt_f32_i32_e32 v156, v4
	v_mul_f32_e32 v136, 0x3f317217, v66
	v_fma_f32 v136, v66, s3, -v136
	v_fmac_f32_e32 v136, 0x3377d1cf, v66
	v_fmac_f32_e32 v136, 0x3f317217, v66
	v_pk_mul_f32 v[152:153], v[152:153], s[10:11] op_sel_hi:[1,0]
	v_pk_mul_f32 v[148:149], v[156:157], v[148:149]
	v_mov_b32_e32 v66, v136
	v_max_f32_e32 v136, 0xc2700000, v66
	v_exp_f32_e32 v152, v152
	v_log_f32_e32 v66, v137
	v_exp_f32_e32 v153, v153
	v_pk_mul_f32 v[148:149], v[148:149], s[10:11] op_sel_hi:[1,0]
	v_mul_f32_e32 v137, 0x3f317217, v66
	v_fma_f32 v137, v66, s3, -v137
	v_fmac_f32_e32 v137, 0x3377d1cf, v66
	v_fmac_f32_e32 v137, 0x3f317217, v66
	v_pk_add_f32 v[152:153], v[152:153], 1.0 op_sel_hi:[1,0]
	v_exp_f32_e32 v148, v148
	v_mov_b32_e32 v66, v137
	v_max_f32_e32 v137, 0xc2700000, v66
	v_rcp_f32_e32 v152, v152
	v_log_f32_e32 v66, v138
	v_rcp_f32_e32 v153, v153
	v_exp_f32_e32 v149, v149
	v_mul_f32_e32 v138, 0x3f317217, v66
	v_fma_f32 v138, v66, s3, -v138
	v_fmac_f32_e32 v138, 0x3377d1cf, v66
	v_fmac_f32_e32 v138, 0x3f317217, v66
	v_pk_fma_f32 v[132:133], v[190:191], v[152:153], v[132:133]
	v_pk_add_f32 v[148:149], v[148:149], 1.0 op_sel_hi:[1,0]
	v_mov_b32_e32 v66, v138
	v_max_f32_e32 v138, 0xc2700000, v66
	v_rcp_f32_e32 v148, v148
	v_log_f32_e32 v66, v139
	v_rcp_f32_e32 v149, v149
	v_mul_f32_e32 v139, 0x3f317217, v66
	v_fma_f32 v139, v66, s3, -v139
	v_fmac_f32_e32 v139, 0x3377d1cf, v66
	v_fmac_f32_e32 v139, 0x3f317217, v66
	v_pk_fma_f32 v[134:135], v[192:193], v[148:149], v[134:135]
	s_nop 0
	v_mov_b32_e32 v66, v139
	v_max_f32_e32 v139, 0xc2700000, v66
	s_nop 0
	v_log_f32_e32 v66, v132
	s_nop 0
	v_mul_f32_e32 v132, 0x3f317217, v66
	v_fma_f32 v132, v66, s3, -v132
	v_fmac_f32_e32 v132, 0x3377d1cf, v66
	v_fmac_f32_e32 v132, 0x3f317217, v66
	s_nop 1
	v_mov_b32_e32 v66, v132
	v_max_f32_e32 v132, 0xc2700000, v66
	s_nop 0
	v_log_f32_e32 v66, v133
	s_nop 0
	v_mul_f32_e32 v133, 0x3f317217, v66
	v_fma_f32 v133, v66, s3, -v133
	v_fmac_f32_e32 v133, 0x3377d1cf, v66
	v_fmac_f32_e32 v133, 0x3f317217, v66
	s_nop 1
	v_mov_b32_e32 v66, v133
	v_max_f32_e32 v133, 0xc2700000, v66
	s_nop 0
	v_log_f32_e32 v66, v134
	s_nop 0
	v_mul_f32_e32 v134, 0x3f317217, v66
	v_fma_f32 v134, v66, s3, -v134
	v_fmac_f32_e32 v134, 0x3377d1cf, v66
	v_fmac_f32_e32 v134, 0x3f317217, v66
	s_nop 1
	v_mov_b32_e32 v66, v134
	v_max_f32_e32 v134, 0xc2700000, v66
	s_nop 0
	v_log_f32_e32 v66, v135
	s_nop 0
	v_mul_f32_e32 v135, 0x3f317217, v66
	v_fma_f32 v135, v66, s3, -v135
	v_fmac_f32_e32 v135, 0x3377d1cf, v66
	v_fmac_f32_e32 v135, 0x3f317217, v66
	s_nop 1
	v_mov_b32_e32 v66, v135
	v_max_f32_e32 v135, 0xc2700000, v66
